# v81 pipeline plus copy-propagated K=16 MFMA operands (U2) and y-row store address strength reduction (V2)
# baseline (speedup 1.0000x reference)
.LBB0_362:
	s_or_b64 exec, exec, s[28:29]
	s_waitcnt lgkmcnt(0)
	s_barrier
	ds_read_b128 v[36:39], v214 offset:18432
	ds_read_b128 v[40:43], v214 offset:9216
	ds_read_b128 v[48:51], v214 offset:18496
	s_waitcnt lgkmcnt(1)
	v_mfma_f32_16x16x32_f16 v[52:55], v[40:43], v[36:39], 0
	ds_read_b128 v[56:59], v214 offset:9280
	ds_read_b128 v[60:63], v214 offset:23040
	ds_read_b128 v[64:67], v214 offset:13824
	ds_read_b128 v[68:71], v214 offset:13888
	ds_read_b128 v[72:75], v214 offset:23104
	v_add_u32_e32 v80, 0x1000, v220
	s_waitcnt lgkmcnt(4)
	v_mfma_f32_16x16x32_f16 v[52:55], v[56:59], v[48:51], v[52:55]
	s_nop 0
	s_nop 0
	s_nop 0
	v_mfma_f32_16x16x32_f16 v[44:47], v[36:39], v[40:43], 0
	s_nop 3
	v_cvt_f16_f32_e32 v0, v52
	v_cvt_f16_f32_e32 v1, v54
	v_cvt_f16_f32_e32 v2, v55
	v_mfma_f32_16x16x32_f16 v[44:47], v[48:51], v[56:59], v[44:47]
	v_cndmask_b32_e64 v79, 0, v0, s[12:13]
	v_cvt_f16_f32_e32 v0, v53
	v_cndmask_b32_e64 v54, 0, v1, s[18:19]
	s_waitcnt lgkmcnt(3)
	v_mfma_f32_16x16x32_f16 v[40:43], v[60:63], v[40:43], 0
	v_cndmask_b32_e64 v55, 0, v2, s[22:23]
	s_nop 1
	v_cndmask_b32_e64 v76, 0, v44, s[10:11]
	v_cndmask_b32_e64 v77, 0, v45, s[14:15]
	s_waitcnt lgkmcnt(2)
	v_mfma_f32_16x16x32_f16 v[36:39], v[36:39], v[64:67], 0
	v_cndmask_b32_e64 v52, 0, v46, s[16:17]
	v_cndmask_b32_e64 v78, 0, v47, s[20:21]
	v_cndmask_b32_e64 v53, v0, 0, s[10:11]
	v_mfma_f32_16x16x32_f16 v[44:47], v[60:63], v[64:67], 0
	v_cvt_pk_f16_f32 v1, v52, v78
	v_cvt_pk_f16_f32 v0, v76, v77
	s_nop 0
	s_waitcnt lgkmcnt(0)
	v_mfma_f32_16x16x32_f16 v[60:63], v[72:75], v[56:59], v[40:43]
	v_add_f32_e32 v56, v215, v76
	v_add_f32_e32 v57, v217, v77
	v_add_f32_e32 v58, v218, v52
	v_mfma_f32_16x16x32_f16 v[40:43], v[48:51], v[68:71], v[36:39]
	v_add_f32_e32 v59, v219, v78
	v_cvt_pk_f16_f32 v67, v26, v27
	v_cvt_pk_f16_f32 v66, v24, v25
	v_pack_b32_f16 v37, v54, v55
	v_pack_b32_f16 v36, v79, v53
	s_nop 0
	s_nop 0
	v_mfma_f32_16x16x32_f16 v[52:55], v[72:75], v[68:71], v[44:47]
	ds_read2_b64 v[68:71], v220 offset0:8 offset1:12
	v_cvt_pk_f16_f32 v65, v30, v31
	v_cvt_pk_f16_f32 v64, v28, v29
	v_mfma_f32_16x16x16_f16 v[48:51], v[0:1], v[36:37], 0
	v_cvt_pk_f16_f32 v45, v58, v59
	v_cvt_pk_f16_f32 v44, v56, v57
	s_nop 0
	v_mfma_f32_16x16x16_f16 v[36:39], v[36:37], v[0:1], 0
	s_nop 0
	s_nop 2
	v_cvt_pk_f16_f32 v1, v50, v51
	v_cvt_pk_f16_f32 v0, v48, v49
	s_nop 0
	s_nop 0
	v_cvt_pk_f16_f32 v49, v38, v39
	v_cvt_pk_f16_f32 v48, v36, v37
	v_mfma_f32_16x16x16_f16 v[44:47], v[0:1], v[44:45], v[56:59]
	s_nop 0
	s_nop 0
	s_nop 0
	v_mfma_f32_16x16x16_f16 v[36:39], v[48:49], v[0:1], 0
	v_cvt_pk_f16_f32 v59, v34, v35
	v_cvt_pk_f16_f32 v58, v32, v33
	v_cvt_pk_f16_f32 v57, v22, v23
	v_mfma_f32_16x16x16_f16 v[48:51], v[0:1], v[48:49], 0
	v_cvt_pk_f16_f32 v56, v20, v21
	s_nop 2
	v_cvt_pk_f16_f32 v1, v38, v39
	v_cvt_pk_f16_f32 v0, v36, v37
	v_cvt_pk_f16_f32 v37, v46, v47
	v_cvt_pk_f16_f32 v36, v44, v45
	s_nop 0
	s_nop 0
	v_cvt_f16_f32_e32 v52, v52
	s_add_i32 s27, s26, 1
	v_mfma_f32_16x16x16_f16 v[44:47], v[0:1], v[36:37], v[44:47]
	v_cvt_pk_f16_f32 v37, v50, v51
	v_cvt_pk_f16_f32 v36, v48, v49
	s_nop 0
	s_nop 0
	v_mfma_f32_16x16x16_f16 v[36:39], v[36:37], v[0:1], 0
	s_nop 2
	v_cvt_pk_f16_f32 v1, v46, v47
	v_cvt_pk_f16_f32 v0, v44, v45
	s_nop 2
	v_cvt_pk_f16_f32 v49, v38, v39
	v_cvt_pk_f16_f32 v48, v36, v37
	ds_read2_b64 v[36:39], v220 offset1:4
	s_waitcnt lgkmcnt(0)
	v_mfma_f32_16x16x32_f16 v[36:39], v[36:39], v[56:59], 0
	v_mfma_f32_16x16x16_f16 v[44:47], v[48:49], v[0:1], v[44:47]
	v_cvt_f16_f32_e32 v0, v60
	v_cvt_f16_f32_e32 v1, v61
	v_cvt_f16_f32_e32 v2, v62
	v_cvt_f16_f32_e32 v48, v63
	v_mfma_f32_16x16x32_f16 v[76:79], v[68:71], v[64:67], v[36:39]
	ds_read2_b64 v[72:75], v80 offset0:64 offset1:68
	ds_read2_b64 v[68:71], v80 offset0:72 offset1:76
	s_nop 0
	ds_read2st64_b64 v[36:39], v221 offset0:20 offset1:25
	v_cndmask_b32_e64 v0, 0, v0, s[10:11]
	v_cndmask_b32_e64 v49, 0, v1, s[14:15]
	v_cndmask_b32_e64 v1, 0, v2, s[16:17]
	v_cndmask_b32_e64 v2, 0, v48, s[20:21]
	v_pack_b32_f16 v1, v1, v2
	v_pack_b32_f16 v0, v0, v49
	s_nop 0
	s_waitcnt lgkmcnt(0)
	v_mov_b32_e32 v60, v36
	v_mov_b32_e32 v61, v37
	s_nop 0
	s_nop 0
	v_cvt_f16_f32_e32 v36, v40
	v_cvt_f16_f32_e32 v40, v42
	v_mfma_f32_16x16x16_f16 v[48:51], v[0:1], v[60:61], v[76:79]
	v_cvt_pk_f16_f32 v1, v46, v47
	v_cvt_pk_f16_f32 v0, v44, v45
	v_cvt_f16_f32_e32 v37, v41
	s_nop 0
	s_nop 0
	s_nop 2
	v_cvt_pk_f16_f32 v77, v50, v51
	v_cvt_pk_f16_f32 v76, v48, v49
	v_cndmask_b32_e64 v88, v40, 0, s[18:19]
	v_mfma_f32_16x16x32_f16 v[56:59], v[72:75], v[56:59], 0
	v_cndmask_b32_e64 v36, v36, 0, s[12:13]
	v_cndmask_b32_e64 v37, 0, v37, s[10:11]
	s_nop 0
	v_mfma_f32_16x16x16_f16 v[44:47], v[0:1], v[76:77], 0
	s_nop 0
	v_mfma_f32_16x16x32_f16 v[56:59], v[68:71], v[64:67], v[56:59]
	s_nop 5
	v_cvt_pk_f16_f32 v1, v46, v47
	v_cvt_pk_f16_f32 v0, v44, v45
	ds_read2_b64 v[44:47], v236 offset1:80
	ds_read_b128 v[48:51], v180
	ds_read_b64 v[76:77], v222 offset:5120
	s_waitcnt lgkmcnt(2)
	s_nop 0
	s_nop 0
	s_waitcnt lgkmcnt(1)
	v_pk_mul_f32 v[50:51], v[22:23], v[50:51]
	v_pk_mul_f32 v[48:49], v[20:21], v[48:49]
	s_nop 1
	v_mfma_f32_16x16x16_f16 v[48:51], v[44:45], v[0:1], v[48:51]
	v_cvt_f16_f32_e32 v80, v43
	v_cndmask_b32_e64 v89, v80, 0, s[22:23]
	s_waitcnt lgkmcnt(0)
	v_mfma_f32_16x16x16_f16 v[40:43], v[76:77], v[60:61], v[48:51]
	s_nop 3
	ds_read_b128 v[48:51], v180 offset:64
	ds_read_b64 v[44:45], v223 offset:5120
	s_nop 0
	s_nop 0
	s_nop 0
	s_waitcnt lgkmcnt(1)
	v_pk_mul_f32 v[50:51], v[34:35], v[50:51]
	v_pk_mul_f32 v[48:49], v[32:33], v[48:49]
	s_nop 0
	s_nop 0
	v_mfma_f32_16x16x16_f16 v[48:51], v[46:47], v[0:1], v[48:51]
	ds_read2_b64 v[76:79], v236 offset0:160 offset1:240
	s_waitcnt lgkmcnt(0)
	v_mov_b32_e32 v84, v76
	v_mfma_f32_16x16x16_f16 v[48:51], v[44:45], v[60:61], v[48:51]
	ds_read_b128 v[44:47], v180 offset:128
	ds_read_b64 v[80:81], v224 offset:5120
	v_mov_b32_e32 v85, v77
	v_pack_b32_f16 v77, v88, v89
	s_nop 0
	s_waitcnt lgkmcnt(1)
	v_pk_mul_f32 v[46:47], v[30:31], v[46:47]
	v_pk_mul_f32 v[44:45], v[28:29], v[44:45]
	s_nop 0
	v_pack_b32_f16 v76, v36, v37
	v_mfma_f32_16x16x16_f16 v[44:47], v[84:85], v[0:1], v[44:47]
	v_cndmask_b32_e64 v36, v52, 0, s[12:13]
	v_cvt_f16_f32_e32 v37, v53
	v_cndmask_b32_e64 v37, 0, v37, s[10:11]
	s_waitcnt lgkmcnt(0)
	v_mfma_f32_16x16x16_f16 v[44:47], v[80:81], v[60:61], v[44:47]
	ds_read_b128 v[80:83], v180 offset:192
	ds_read_b64 v[84:85], v225 offset:5120
	v_pack_b32_f16 v72, v36, v37
	ds_read_b128 v[68:71], v226 offset:9216
	ds_read_b128 v[94:97], v226 offset:9280
	s_waitcnt lgkmcnt(3)
	v_pk_mul_f32 v[82:83], v[26:27], v[82:83]
	v_pk_mul_f32 v[80:81], v[24:25], v[80:81]
	ds_read_b128 v[64:67], v226 offset:18432
	ds_read_b128 v[98:101], v226 offset:23104
	v_mfma_f32_16x16x16_f16 v[78:81], v[78:79], v[0:1], v[80:83]
	ds_read_b128 v[90:93], v226 offset:18496
	s_nop 1
	v_cvt_f16_f32_e32 v82, v54
	v_cvt_f16_f32_e32 v83, v55
	s_waitcnt lgkmcnt(5)
	v_mfma_f32_16x16x16_f16 v[52:55], v[84:85], v[60:61], v[78:81]
	ds_read_b128 v[86:89], v226 offset:13824
	s_nop 1
	v_cndmask_b32_e64 v78, v82, 0, s[18:19]
	v_cndmask_b32_e64 v79, v83, 0, s[22:23]
	v_pack_b32_f16 v73, v78, v79
	s_nop 0
	s_nop 0
	v_add_u32_e32 v80, s77, v122
	v_add_u32_e32 v81, s76, v235
	v_mfma_f32_16x16x16_f16 v[56:59], v[76:77], v[0:1], v[56:59]
	ds_read_b128 v[76:79], v226 offset:23040
	v_subrev_u32_e32 v102, 64, v80
	v_add_u32_e32 v0, 0xff, v81
	v_mfma_f32_16x16x16_f16 v[58:61], v[72:73], v[60:61], v[56:59]
	v_cndmask_b32_e64 v0, v0, v102, s[2:3]
	v_add_u32_e32 v0, v0, v173
	s_not_b32 s30, s2
	s_xor_b32 s31, s91, s30
	s_sub_u32 s31, s31, s30
	v_mad_i64_i32 v[0:1], s[28:29], v0, s91, v[126:127]
	v_mov_b64_e32 v[248:249], v[0:1]
	s_waitcnt lgkmcnt(4)
	v_mfma_f32_16x16x32_f16 v[82:85], v[68:71], v[64:67], 0
	s_nop 2
	v_cvt_f16_f32_e32 v2, v58
	v_cvt_f16_f32_e32 v60, v60
	global_store_short v[0:1], v2, off
	s_nop 0
	s_nop 0
	v_cvt_f16_f32_e32 v2, v59
	ds_read_b128 v[56:59], v226 offset:13888
	v_mfma_f32_16x16x32_f16 v[72:75], v[64:67], v[68:71], 0
	s_nop 0
	s_nop 0
	s_mul_i32 s52, s31, 1
	s_mul_hi_i32 s53, s31, 1
	v_lshl_add_u64 v[0:1], v[248:249], 0, s[52:53]
	s_waitcnt lgkmcnt(2)
	v_mfma_f32_16x16x32_f16 v[62:65], v[64:67], v[86:89], 0
	global_store_short v[0:1], v2, off
	s_nop 0
	s_nop 0
	v_mfma_f32_16x16x32_f16 v[82:85], v[94:97], v[90:93], v[82:85]
	s_nop 0
	s_nop 0
	s_waitcnt lgkmcnt(1)
	v_mfma_f32_16x16x32_f16 v[68:71], v[76:79], v[68:71], 0
	v_mfma_f32_16x16x32_f16 v[86:89], v[76:79], v[86:89], 0
	s_nop 2
	v_cvt_f16_f32_e32 v1, v82
	v_cvt_f16_f32_e32 v2, v83
	v_cvt_f16_f32_e32 v66, v85
	v_mfma_f32_16x16x32_f16 v[72:75], v[90:93], v[94:97], v[72:75]
	s_nop 0
	v_cndmask_b32_e64 v66, 0, v66, s[22:23]
	s_waitcnt lgkmcnt(0)
	v_mfma_f32_16x16x32_f16 v[76:79], v[90:93], v[56:59], v[62:65]
	s_nop 0
	s_nop 2
	v_cndmask_b32_e64 v0, 0, v72, s[10:11]
	v_cndmask_b32_e64 v37, 0, v73, s[14:15]
	v_cvt_f16_f32_e32 v63, v84
	v_mfma_f32_16x16x32_f16 v[94:97], v[98:101], v[94:97], v[68:71]
	v_cndmask_b32_e64 v64, 0, v74, s[16:17]
	v_cndmask_b32_e64 v65, 0, v75, s[20:21]
	v_cndmask_b32_e64 v63, 0, v63, s[18:19]
	v_cndmask_b32_e64 v68, 0, v1, s[12:13]
	v_cndmask_b32_e64 v69, v2, 0, s[10:11]
	v_add_f32_e32 v62, v215, v0
	v_cvt_pk_f16_f32 v1, v64, v65
	v_cvt_pk_f16_f32 v0, v0, v37
	s_nop 0
	v_pack_b32_f16 v67, v63, v66
	v_pack_b32_f16 v66, v68, v69
	s_nop 0
	s_nop 0
	v_add_f32_e32 v63, v217, v37
	v_add_f32_e32 v64, v218, v64
	v_mfma_f32_16x16x16_f16 v[70:73], v[0:1], v[66:67], 0
	v_add_f32_e32 v65, v219, v65
	v_cvt_pk_f16_f32 v83, v64, v65
	v_cvt_pk_f16_f32 v82, v62, v63
	v_mfma_f32_16x16x16_f16 v[66:69], v[66:67], v[0:1], 0
	s_nop 0
	s_nop 2
	v_cvt_pk_f16_f32 v0, v70, v71
	s_nop 0
	s_nop 0
	v_cvt_pk_f16_f32 v1, v72, v73
	v_cvt_pk_f16_f32 v69, v68, v69
	v_cvt_pk_f16_f32 v68, v66, v67
	v_mfma_f32_16x16x16_f16 v[62:65], v[0:1], v[82:83], v[62:65]
	s_mul_i32 s52, s31, 2
	s_mul_hi_i32 s53, s31, 2
	v_lshl_add_u64 v[36:37], v[248:249], 0, s[52:53]
	global_store_short v[36:37], v60, off
	v_mfma_f32_16x16x16_f16 v[72:75], v[68:69], v[0:1], 0
	v_cvt_f16_f32_e32 v82, v61
	v_subrev_u32_e32 v36, 61, v80
	v_xad_u32 v37, v102, -4, v166
	v_mfma_f32_16x16x16_f16 v[66:69], v[0:1], v[68:69], 0
	s_nop 0
	v_cvt_pk_f16_f32 v71, v64, v65
	s_nop 1
	v_cvt_pk_f16_f32 v1, v74, v75
	v_cvt_pk_f16_f32 v0, v72, v73
	v_mfma_f32_16x16x32_f16 v[56:59], v[98:101], v[56:59], v[86:89]
	v_cvt_pk_f16_f32 v70, v62, v63
	s_nop 0
	s_nop 0
	v_cvt_pk_f16_f32 v85, v68, v69
	v_cvt_pk_f16_f32 v84, v66, v67
	s_nop 0
	s_nop 0
	v_mfma_f32_16x16x16_f16 v[88:91], v[0:1], v[70:71], v[62:65]
	ds_read2_b64 v[68:71], v227 offset1:4
	ds_read2_b64 v[72:75], v227 offset0:8 offset1:12
	v_cndmask_b32_e64 v36, v37, v36, s[2:3]
	v_mfma_f32_16x16x16_f16 v[60:63], v[84:85], v[0:1], 0
	v_add_u32_e32 v83, v36, v173
	s_nop 2
	v_cvt_pk_f16_f32 v1, v90, v91
	v_cvt_pk_f16_f32 v0, v88, v89
	v_cvt_pk_f16_f32 v67, v54, v55
	v_cvt_pk_f16_f32 v66, v52, v53
	v_cvt_pk_f16_f32 v85, v62, v63
	v_cvt_pk_f16_f32 v84, v60, v61
	v_cvt_pk_f16_f32 v63, v50, v51
	v_cvt_pk_f16_f32 v62, v48, v49
	v_cvt_pk_f16_f32 v61, v42, v43
	v_cvt_pk_f16_f32 v60, v40, v41
	v_cvt_pk_f16_f32 v65, v46, v47
	v_cvt_pk_f16_f32 v64, v44, v45
	s_waitcnt lgkmcnt(1)
	v_mfma_f32_16x16x32_f16 v[68:71], v[68:71], v[60:63], 0
	v_add_u32_e32 v36, 0x1000, v227
	s_nop 0
	v_cvt_f16_f32_e32 v76, v76
	s_waitcnt lgkmcnt(0)
	v_mfma_f32_16x16x32_f16 v[98:101], v[72:75], v[64:67], v[68:71]
	ds_read2_b64 v[72:75], v36 offset0:64 offset1:68
	s_nop 1
	ds_read2_b64 v[68:71], v36 offset0:72 offset1:76
	v_cvt_f16_f32_e32 v36, v97
	v_cvt_f16_f32_e32 v97, v77
	v_mfma_f32_16x16x16_f16 v[84:87], v[84:85], v[0:1], v[88:91]
	v_cvt_f16_f32_e32 v0, v94
	v_cvt_f16_f32_e32 v1, v95
	v_cvt_f16_f32_e32 v2, v96
	v_cndmask_b32_e64 v96, v76, 0, s[12:13]
	v_cndmask_b32_e64 v0, 0, v0, s[10:11]
	v_cndmask_b32_e64 v37, 0, v1, s[14:15]
	v_cndmask_b32_e64 v1, 0, v2, s[16:17]
	v_cndmask_b32_e64 v2, 0, v36, s[20:21]
	v_pack_b32_f16 v1, v1, v2
	v_pack_b32_f16 v0, v0, v37
	s_nop 0
	s_nop 0
	s_nop 0
	s_nop 0
	s_nop 0
	v_mov_b32_e32 v94, v3
	v_mov_b32_e32 v95, v3
	v_mfma_f32_16x16x16_f16 v[88:91], v[0:1], v[38:39], v[98:101]
	v_cvt_pk_f16_f32 v1, v86, v87
	v_cvt_pk_f16_f32 v0, v84, v85
	v_cvt_f16_f32_e32 v56, v56
	v_cvt_f16_f32_e32 v98, v78
	v_cvt_f16_f32_e32 v99, v79
	s_nop 2
	v_cvt_pk_f16_f32 v91, v90, v91
	v_cvt_pk_f16_f32 v90, v88, v89
	v_cndmask_b32_e64 v97, 0, v97, s[10:11]
	v_cndmask_b32_e64 v98, v98, 0, s[18:19]
	v_mfma_f32_16x16x16_f16 v[84:87], v[0:1], v[90:91], 0
	v_add_u32_e32 v2, 0x800, v236
	v_mov_b32_e32 v90, v3
	v_mov_b32_e32 v91, v3
	v_cndmask_b32_e64 v99, v99, 0, s[22:23]
	s_nop 3
	v_cvt_pk_f16_f32 v1, v86, v87
	v_cvt_pk_f16_f32 v0, v84, v85
	ds_read2_b64 v[84:87], v2 offset0:64 offset1:144
	ds_read_b128 v[76:79], v180 offset:256
	ds_read_b64 v[88:89], v228 offset:5120
	s_nop 0
	s_waitcnt lgkmcnt(2)
	v_mov_b32_e32 v92, v84
	v_mov_b32_e32 v93, v85
	s_waitcnt lgkmcnt(1)
	v_pk_mul_f32 v[42:43], v[42:43], v[78:79]
	v_pk_mul_f32 v[40:41], v[40:41], v[76:77]
	ds_read_b128 v[76:79], v180 offset:320
	ds_read_b64 v[84:85], v229 offset:5120
	v_mfma_f32_16x16x16_f16 v[40:43], v[92:93], v[0:1], v[40:43]
	s_waitcnt lgkmcnt(1)
	v_pk_mul_f32 v[48:49], v[48:49], v[76:77]
	v_add_u32_e32 v76, 0xc00, v236
	v_mfma_f32_16x16x16_f16 v[40:43], v[88:89], v[38:39], v[40:43]
	s_nop 0
	s_nop 0
	v_pk_mul_f32 v[50:51], v[50:51], v[78:79]
	s_nop 0
	s_nop 0
	ds_read2_b64 v[76:79], v76 offset0:96 offset1:176
	v_mfma_f32_16x16x16_f16 v[48:51], v[86:87], v[0:1], v[48:51]
	s_waitcnt lgkmcnt(0)
	v_mov_b32_e32 v92, v76
	v_mfma_f32_16x16x16_f16 v[48:51], v[84:85], v[38:39], v[48:51]
	ds_read_b128 v[84:87], v180 offset:384
	ds_read_b64 v[88:89], v230 offset:5120
	v_mov_b32_e32 v93, v77
	v_pack_b32_f16 v76, v96, v97
	v_cndmask_b32_e64 v96, v56, 0, s[12:13]
	s_waitcnt lgkmcnt(1)
	v_pk_mul_f32 v[46:47], v[46:47], v[86:87]
	v_pk_mul_f32 v[44:45], v[44:45], v[84:85]
	v_cvt_f16_f32_e32 v56, v57
	v_cvt_f16_f32_e32 v57, v58
	v_mfma_f32_16x16x16_f16 v[44:47], v[92:93], v[0:1], v[44:47]
	v_cvt_f16_f32_e32 v58, v59
	v_mov_b32_e32 v92, v78
	v_mov_b32_e32 v93, v79
	s_waitcnt lgkmcnt(0)
	v_mfma_f32_16x16x16_f16 v[44:47], v[88:89], v[38:39], v[44:47]
	ds_read_b128 v[84:87], v180 offset:448
	ds_read_b64 v[88:89], v231 offset:5120
	v_cndmask_b32_e64 v78, v57, 0, s[18:19]
	v_cndmask_b32_e64 v79, v58, 0, s[22:23]
	v_pack_b32_f16 v77, v98, v99
	s_waitcnt lgkmcnt(1)
	v_pk_mul_f32 v[52:53], v[52:53], v[84:85]
	v_cndmask_b32_e64 v84, 0, v56, s[10:11]
	v_mfma_f32_16x16x32_f16 v[56:59], v[72:75], v[60:63], 0
	v_pack_b32_f16 v61, v78, v79
	v_mov_b32_e32 v78, v3
	v_mov_b32_e32 v79, v3
	v_mfma_f32_16x16x32_f16 v[56:59], v[68:71], v[64:67], v[56:59]
	v_mul_f32_e64 v54, v54, v86
	v_mul_f32_e64 v55, v55, v87
	v_pack_b32_f16 v60, v96, v84
	s_nop 0
	s_nop 0
	v_mfma_f32_16x16x16_f16 v[52:55], v[92:93], v[0:1], v[52:55]
	v_mfma_f32_16x16x16_f16 v[56:59], v[76:77], v[0:1], v[56:59]
	s_mul_i32 s52, s31, 3
	s_mul_hi_i32 s53, s31, 3
	v_lshl_add_u64 v[0:1], v[248:249], 0, s[52:53]
	global_store_short v[0:1], v82, off
	s_waitcnt lgkmcnt(0)
	v_mfma_f32_16x16x16_f16 v[52:55], v[88:89], v[38:39], v[52:55]
	s_nop 0
	s_nop 0
	s_nop 0
	v_mfma_f32_16x16x16_f16 v[36:39], v[60:61], v[38:39], v[56:59]
	s_nop 0
	s_mul_i32 s52, s31, 16
	s_mul_hi_i32 s53, s31, 16
	v_lshl_add_u64 v[0:1], v[248:249], 0, s[52:53]
	s_nop 5
	v_cvt_f16_f32_e32 v2, v36
	global_store_short v[0:1], v2, off
	s_nop 0
	s_nop 0
	v_cvt_f16_f32_e32 v2, v37
	s_nop 0
	s_nop 0
	s_mul_i32 s52, s31, 17
	s_mul_hi_i32 s53, s31, 17
	v_lshl_add_u64 v[0:1], v[248:249], 0, s[52:53]
	global_store_short v[0:1], v2, off
	s_nop 0
	s_nop 0
	v_cvt_f16_f32_e32 v2, v38
	s_nop 0
	s_nop 0
	s_mul_i32 s52, s31, 18
	s_mul_hi_i32 s53, s31, 18
	v_lshl_add_u64 v[0:1], v[248:249], 0, s[52:53]
	global_store_short v[0:1], v2, off
	s_nop 0
	s_nop 0
	s_nop 0
	v_cvt_f16_f32_e32 v2, v39
	s_nop 0
	s_mul_i32 s52, s31, 19
	s_mul_hi_i32 s53, s31, 19
	v_lshl_add_u64 v[0:1], v[248:249], 0, s[52:53]
	s_mov_b64 s[28:29], 0
	global_store_short v[0:1], v2, off

.LBB0_462:
	s_or_b64 exec, exec, s[26:27]
	s_waitcnt lgkmcnt(0)
	s_barrier
	ds_read_b128 v[36:39], v210 offset:18432
	ds_read_b128 v[40:43], v210 offset:9216
	ds_read_b128 v[48:51], v210 offset:18496
	s_waitcnt lgkmcnt(1)
	v_mfma_f32_16x16x32_f16 v[52:55], v[40:43], v[36:39], 0
	ds_read_b128 v[56:59], v210 offset:9280
	ds_read_b128 v[60:63], v210 offset:23040
	ds_read_b128 v[64:67], v210 offset:13824
	ds_read_b128 v[68:71], v210 offset:13888
	ds_read_b128 v[72:75], v210 offset:23104
	v_add_u32_e32 v80, 0x1000, v215
	s_waitcnt lgkmcnt(4)
	v_mfma_f32_16x16x32_f16 v[52:55], v[56:59], v[48:51], v[52:55]
	s_nop 0
	s_nop 0
	s_nop 0
	v_mfma_f32_16x16x32_f16 v[44:47], v[36:39], v[40:43], 0
	s_nop 3
	v_cvt_f16_f32_e32 v0, v52
	v_cvt_f16_f32_e32 v1, v54
	v_cvt_f16_f32_e32 v2, v55
	v_mfma_f32_16x16x32_f16 v[44:47], v[48:51], v[56:59], v[44:47]
	v_cndmask_b32_e64 v79, 0, v0, s[12:13]
	v_cvt_f16_f32_e32 v0, v53
	v_cndmask_b32_e64 v54, 0, v1, s[18:19]
	s_waitcnt lgkmcnt(3)
	v_mfma_f32_16x16x32_f16 v[40:43], v[60:63], v[40:43], 0
	v_cndmask_b32_e64 v55, 0, v2, s[22:23]
	s_nop 1
	v_cndmask_b32_e64 v76, 0, v44, s[10:11]
	v_cndmask_b32_e64 v77, 0, v45, s[14:15]
	s_waitcnt lgkmcnt(2)
	v_mfma_f32_16x16x32_f16 v[36:39], v[36:39], v[64:67], 0
	v_cndmask_b32_e64 v52, 0, v46, s[16:17]
	v_cndmask_b32_e64 v78, 0, v47, s[20:21]
	v_cndmask_b32_e64 v53, v0, 0, s[10:11]
	v_mfma_f32_16x16x32_f16 v[44:47], v[60:63], v[64:67], 0
	v_cvt_pk_f16_f32 v1, v52, v78
	v_cvt_pk_f16_f32 v0, v76, v77
	s_nop 0
	s_waitcnt lgkmcnt(0)
	v_mfma_f32_16x16x32_f16 v[60:63], v[72:75], v[56:59], v[40:43]
	v_add_f32_e32 v56, v211, v76
	v_add_f32_e32 v57, v212, v77
	v_add_f32_e32 v58, v213, v52
	v_mfma_f32_16x16x32_f16 v[40:43], v[48:51], v[68:71], v[36:39]
	v_add_f32_e32 v59, v214, v78
	v_cvt_pk_f16_f32 v67, v18, v19
	v_cvt_pk_f16_f32 v66, v16, v17
	v_pack_b32_f16 v37, v54, v55
	v_pack_b32_f16 v36, v79, v53
	s_nop 0
	s_nop 0
	v_mfma_f32_16x16x32_f16 v[52:55], v[72:75], v[68:71], v[44:47]
	ds_read2_b64 v[68:71], v215 offset0:8 offset1:12
	v_cvt_pk_f16_f32 v65, v14, v15
	v_cvt_pk_f16_f32 v64, v12, v13
	v_mfma_f32_16x16x16_f16 v[48:51], v[0:1], v[36:37], 0
	v_cvt_pk_f16_f32 v45, v58, v59
	v_cvt_pk_f16_f32 v44, v56, v57
	s_nop 0
	v_mfma_f32_16x16x16_f16 v[36:39], v[36:37], v[0:1], 0
	s_nop 0
	s_nop 2
	v_cvt_pk_f16_f32 v1, v50, v51
	v_cvt_pk_f16_f32 v0, v48, v49
	s_nop 0
	s_nop 0
	v_cvt_pk_f16_f32 v49, v38, v39
	v_cvt_pk_f16_f32 v48, v36, v37
	v_mfma_f32_16x16x16_f16 v[44:47], v[0:1], v[44:45], v[56:59]
	s_nop 0
	s_nop 0
	s_nop 0
	v_mfma_f32_16x16x16_f16 v[36:39], v[48:49], v[0:1], 0
	v_cvt_pk_f16_f32 v59, v10, v11
	v_cvt_pk_f16_f32 v58, v8, v9
	v_cvt_pk_f16_f32 v57, v6, v7
	v_mfma_f32_16x16x16_f16 v[48:51], v[0:1], v[48:49], 0
	v_cvt_pk_f16_f32 v56, v4, v5
	s_nop 2
	v_cvt_pk_f16_f32 v1, v38, v39
	v_cvt_pk_f16_f32 v0, v36, v37
	v_cvt_pk_f16_f32 v37, v46, v47
	v_cvt_pk_f16_f32 v36, v44, v45
	s_nop 0
	s_nop 0
	v_cvt_f16_f32_e32 v52, v52
	s_add_i32 s28, s76, 1
	v_mfma_f32_16x16x16_f16 v[44:47], v[0:1], v[36:37], v[44:47]
	v_cvt_pk_f16_f32 v37, v50, v51
	v_cvt_pk_f16_f32 v36, v48, v49
	s_nop 0
	s_nop 0
	v_mfma_f32_16x16x16_f16 v[36:39], v[36:37], v[0:1], 0
	s_nop 2
	v_cvt_pk_f16_f32 v1, v46, v47
	v_cvt_pk_f16_f32 v0, v44, v45
	s_nop 2
	v_cvt_pk_f16_f32 v49, v38, v39
	v_cvt_pk_f16_f32 v48, v36, v37
	ds_read2_b64 v[36:39], v215 offset1:4
	s_waitcnt lgkmcnt(0)
	v_mfma_f32_16x16x32_f16 v[36:39], v[36:39], v[56:59], 0
	v_mfma_f32_16x16x16_f16 v[44:47], v[48:49], v[0:1], v[44:47]
	v_cvt_f16_f32_e32 v0, v60
	v_cvt_f16_f32_e32 v1, v61
	v_cvt_f16_f32_e32 v2, v62
	v_cvt_f16_f32_e32 v48, v63
	v_mfma_f32_16x16x32_f16 v[76:79], v[68:71], v[64:67], v[36:39]
	ds_read2_b64 v[72:75], v80 offset0:64 offset1:68
	ds_read2_b64 v[68:71], v80 offset0:72 offset1:76
	s_nop 0
	ds_read2st64_b64 v[36:39], v216 offset0:20 offset1:25
	v_cndmask_b32_e64 v0, 0, v0, s[10:11]
	v_cndmask_b32_e64 v49, 0, v1, s[14:15]
	v_cndmask_b32_e64 v1, 0, v2, s[16:17]
	v_cndmask_b32_e64 v2, 0, v48, s[20:21]
	v_pack_b32_f16 v1, v1, v2
	v_pack_b32_f16 v0, v0, v49
	s_nop 0
	s_waitcnt lgkmcnt(0)
	v_mov_b32_e32 v60, v36
	v_mov_b32_e32 v61, v37
	s_nop 0
	s_nop 0
	v_cvt_f16_f32_e32 v36, v40
	v_cvt_f16_f32_e32 v40, v42
	v_mfma_f32_16x16x16_f16 v[48:51], v[0:1], v[60:61], v[76:79]
	v_cvt_pk_f16_f32 v1, v46, v47
	v_cvt_pk_f16_f32 v0, v44, v45
	v_cvt_f16_f32_e32 v37, v41
	s_nop 0
	s_nop 0
	s_nop 2
	v_cvt_pk_f16_f32 v77, v50, v51
	v_cvt_pk_f16_f32 v76, v48, v49
	v_cndmask_b32_e64 v88, v40, 0, s[18:19]
	v_mfma_f32_16x16x32_f16 v[56:59], v[72:75], v[56:59], 0
	v_cndmask_b32_e64 v36, v36, 0, s[12:13]
	v_cndmask_b32_e64 v37, 0, v37, s[10:11]
	s_nop 0
	v_mfma_f32_16x16x16_f16 v[44:47], v[0:1], v[76:77], 0
	s_nop 0
	v_mfma_f32_16x16x32_f16 v[56:59], v[68:71], v[64:67], v[56:59]
	s_nop 5
	v_cvt_pk_f16_f32 v1, v46, v47
	v_cvt_pk_f16_f32 v0, v44, v45
	ds_read2_b64 v[44:47], v231 offset1:80
	ds_read_b128 v[48:51], v176
	ds_read_b64 v[76:77], v217 offset:5120
	s_waitcnt lgkmcnt(2)
	s_nop 0
	s_nop 0
	s_waitcnt lgkmcnt(1)
	v_pk_mul_f32 v[50:51], v[6:7], v[50:51]
	v_pk_mul_f32 v[48:49], v[4:5], v[48:49]
	s_nop 1
	v_mfma_f32_16x16x16_f16 v[48:51], v[44:45], v[0:1], v[48:51]
	v_cvt_f16_f32_e32 v80, v43
	v_cndmask_b32_e64 v89, v80, 0, s[22:23]
	s_waitcnt lgkmcnt(0)
	v_mfma_f32_16x16x16_f16 v[40:43], v[76:77], v[60:61], v[48:51]
	s_nop 3
	ds_read_b128 v[48:51], v176 offset:64
	ds_read_b64 v[44:45], v218 offset:5120
	s_nop 0
	s_nop 0
	s_nop 0
	s_waitcnt lgkmcnt(1)
	v_pk_mul_f32 v[50:51], v[10:11], v[50:51]
	v_pk_mul_f32 v[48:49], v[8:9], v[48:49]
	s_nop 0
	s_nop 0
	v_mfma_f32_16x16x16_f16 v[48:51], v[46:47], v[0:1], v[48:51]
	ds_read2_b64 v[76:79], v231 offset0:160 offset1:240
	s_waitcnt lgkmcnt(0)
	v_mov_b32_e32 v84, v76
	v_mfma_f32_16x16x16_f16 v[48:51], v[44:45], v[60:61], v[48:51]
	ds_read_b128 v[44:47], v176 offset:128
	ds_read_b64 v[80:81], v219 offset:5120
	v_mov_b32_e32 v85, v77
	v_pack_b32_f16 v77, v88, v89
	s_nop 0
	s_waitcnt lgkmcnt(1)
	v_pk_mul_f32 v[46:47], v[14:15], v[46:47]
	v_pk_mul_f32 v[44:45], v[12:13], v[44:45]
	s_nop 0
	v_pack_b32_f16 v76, v36, v37
	v_mfma_f32_16x16x16_f16 v[44:47], v[84:85], v[0:1], v[44:47]
	v_cndmask_b32_e64 v36, v52, 0, s[12:13]
	v_cvt_f16_f32_e32 v37, v53
	v_cndmask_b32_e64 v37, 0, v37, s[10:11]
	s_waitcnt lgkmcnt(0)
	v_mfma_f32_16x16x16_f16 v[44:47], v[80:81], v[60:61], v[44:47]
	ds_read_b128 v[80:83], v176 offset:192
	ds_read_b64 v[84:85], v220 offset:5120
	v_pack_b32_f16 v72, v36, v37
	ds_read_b128 v[68:71], v221 offset:9216
	ds_read_b128 v[94:97], v221 offset:9280
	s_waitcnt lgkmcnt(3)
	v_pk_mul_f32 v[82:83], v[18:19], v[82:83]
	v_pk_mul_f32 v[80:81], v[16:17], v[80:81]
	ds_read_b128 v[64:67], v221 offset:18432
	ds_read_b128 v[98:101], v221 offset:23104
	v_mfma_f32_16x16x16_f16 v[78:81], v[78:79], v[0:1], v[80:83]
	ds_read_b128 v[90:93], v221 offset:18496
	s_nop 1
	v_cvt_f16_f32_e32 v82, v54
	v_cvt_f16_f32_e32 v83, v55
	s_waitcnt lgkmcnt(5)
	v_mfma_f32_16x16x16_f16 v[52:55], v[84:85], v[60:61], v[78:81]
	ds_read_b128 v[86:89], v221 offset:13824
	s_nop 1
	v_cndmask_b32_e64 v78, v82, 0, s[18:19]
	v_cndmask_b32_e64 v79, v83, 0, s[22:23]
	v_pack_b32_f16 v73, v78, v79
	s_nop 0
	s_nop 0
	v_add_u32_e32 v80, s71, v153
	v_add_u32_e32 v81, s70, v230
	v_mfma_f32_16x16x16_f16 v[56:59], v[76:77], v[0:1], v[56:59]
	ds_read_b128 v[76:79], v221 offset:23040
	v_subrev_u32_e32 v102, 64, v80
	v_add_u32_e32 v0, 0x7ff, v81
	v_mfma_f32_16x16x16_f16 v[58:61], v[72:73], v[60:61], v[56:59]
	v_cndmask_b32_e64 v0, v0, v102, s[2:3]
	v_add_u32_e32 v0, v0, v151
	s_not_b32 s30, s2
	s_xor_b32 s31, s91, s30
	s_sub_u32 s31, s31, s30
	v_mad_i64_i32 v[0:1], s[26:27], v0, s91, v[122:123]
	v_mov_b64_e32 v[248:249], v[0:1]
	s_waitcnt lgkmcnt(4)
	v_mfma_f32_16x16x32_f16 v[82:85], v[68:71], v[64:67], 0
	s_nop 2
	v_cvt_f16_f32_e32 v2, v58
	v_cvt_f16_f32_e32 v60, v60
	global_store_short v[0:1], v2, off
	s_nop 0
	s_nop 0
	v_cvt_f16_f32_e32 v2, v59
	ds_read_b128 v[56:59], v221 offset:13888
	v_mfma_f32_16x16x32_f16 v[72:75], v[64:67], v[68:71], 0
	s_nop 0
	s_nop 0
	s_mul_i32 s52, s31, 1
	s_mul_hi_i32 s53, s31, 1
	v_lshl_add_u64 v[0:1], v[248:249], 0, s[52:53]
	s_waitcnt lgkmcnt(2)
	v_mfma_f32_16x16x32_f16 v[62:65], v[64:67], v[86:89], 0
	global_store_short v[0:1], v2, off
	s_nop 0
	s_nop 0
	v_mfma_f32_16x16x32_f16 v[82:85], v[94:97], v[90:93], v[82:85]
	s_nop 0
	s_nop 0
	s_waitcnt lgkmcnt(1)
	v_mfma_f32_16x16x32_f16 v[68:71], v[76:79], v[68:71], 0
	v_mfma_f32_16x16x32_f16 v[86:89], v[76:79], v[86:89], 0
	s_nop 2
	v_cvt_f16_f32_e32 v1, v82
	v_cvt_f16_f32_e32 v2, v83
	v_cvt_f16_f32_e32 v66, v85
	v_mfma_f32_16x16x32_f16 v[72:75], v[90:93], v[94:97], v[72:75]
	s_nop 0
	v_cndmask_b32_e64 v66, 0, v66, s[22:23]
	s_waitcnt lgkmcnt(0)
	v_mfma_f32_16x16x32_f16 v[76:79], v[90:93], v[56:59], v[62:65]
	s_nop 0
	s_nop 2
	v_cndmask_b32_e64 v0, 0, v72, s[10:11]
	v_cndmask_b32_e64 v37, 0, v73, s[14:15]
	v_cvt_f16_f32_e32 v63, v84
	v_mfma_f32_16x16x32_f16 v[94:97], v[98:101], v[94:97], v[68:71]
	v_cndmask_b32_e64 v64, 0, v74, s[16:17]
	v_cndmask_b32_e64 v65, 0, v75, s[20:21]
	v_cndmask_b32_e64 v63, 0, v63, s[18:19]
	v_cndmask_b32_e64 v68, 0, v1, s[12:13]
	v_cndmask_b32_e64 v69, v2, 0, s[10:11]
	v_add_f32_e32 v62, v211, v0
	v_cvt_pk_f16_f32 v1, v64, v65
	v_cvt_pk_f16_f32 v0, v0, v37
	s_nop 0
	v_pack_b32_f16 v67, v63, v66
	v_pack_b32_f16 v66, v68, v69
	s_nop 0
	s_nop 0
	v_add_f32_e32 v63, v212, v37
	v_add_f32_e32 v64, v213, v64
	v_mfma_f32_16x16x16_f16 v[70:73], v[0:1], v[66:67], 0
	v_add_f32_e32 v65, v214, v65
	v_cvt_pk_f16_f32 v83, v64, v65
	v_cvt_pk_f16_f32 v82, v62, v63
	v_mfma_f32_16x16x16_f16 v[66:69], v[66:67], v[0:1], 0
	s_nop 0
	s_nop 2
	v_cvt_pk_f16_f32 v0, v70, v71
	s_nop 0
	s_nop 0
	v_cvt_pk_f16_f32 v1, v72, v73
	v_cvt_pk_f16_f32 v69, v68, v69
	v_cvt_pk_f16_f32 v68, v66, v67
	v_mfma_f32_16x16x16_f16 v[62:65], v[0:1], v[82:83], v[62:65]
	s_mul_i32 s52, s31, 2
	s_mul_hi_i32 s53, s31, 2
	v_lshl_add_u64 v[36:37], v[248:249], 0, s[52:53]
	global_store_short v[36:37], v60, off
	v_mfma_f32_16x16x16_f16 v[72:75], v[68:69], v[0:1], 0
	v_cvt_f16_f32_e32 v82, v61
	v_subrev_u32_e32 v36, 61, v80
	v_xad_u32 v37, v102, -4, v170
	v_mfma_f32_16x16x16_f16 v[66:69], v[0:1], v[68:69], 0
	s_nop 0
	v_cvt_pk_f16_f32 v71, v64, v65
	s_nop 1
	v_cvt_pk_f16_f32 v1, v74, v75
	v_cvt_pk_f16_f32 v0, v72, v73
	v_mfma_f32_16x16x32_f16 v[56:59], v[98:101], v[56:59], v[86:89]
	v_cvt_pk_f16_f32 v70, v62, v63
	s_nop 0
	s_nop 0
	v_cvt_pk_f16_f32 v85, v68, v69
	v_cvt_pk_f16_f32 v84, v66, v67
	s_nop 0
	s_nop 0
	v_mfma_f32_16x16x16_f16 v[88:91], v[0:1], v[70:71], v[62:65]
	ds_read2_b64 v[68:71], v222 offset1:4
	ds_read2_b64 v[72:75], v222 offset0:8 offset1:12
	v_cndmask_b32_e64 v36, v37, v36, s[2:3]
	v_mfma_f32_16x16x16_f16 v[60:63], v[84:85], v[0:1], 0
	v_add_u32_e32 v83, v36, v151
	s_nop 2
	v_cvt_pk_f16_f32 v1, v90, v91
	v_cvt_pk_f16_f32 v0, v88, v89
	v_cvt_pk_f16_f32 v67, v54, v55
	v_cvt_pk_f16_f32 v66, v52, v53
	v_cvt_pk_f16_f32 v85, v62, v63
	v_cvt_pk_f16_f32 v84, v60, v61
	v_cvt_pk_f16_f32 v63, v50, v51
	v_cvt_pk_f16_f32 v62, v48, v49
	v_cvt_pk_f16_f32 v61, v42, v43
	v_cvt_pk_f16_f32 v60, v40, v41
	v_cvt_pk_f16_f32 v65, v46, v47
	v_cvt_pk_f16_f32 v64, v44, v45
	s_waitcnt lgkmcnt(1)
	v_mfma_f32_16x16x32_f16 v[68:71], v[68:71], v[60:63], 0
	v_add_u32_e32 v36, 0x1000, v222
	s_nop 0
	v_cvt_f16_f32_e32 v76, v76
	s_waitcnt lgkmcnt(0)
	v_mfma_f32_16x16x32_f16 v[98:101], v[72:75], v[64:67], v[68:71]
	ds_read2_b64 v[72:75], v36 offset0:64 offset1:68
	s_nop 1
	ds_read2_b64 v[68:71], v36 offset0:72 offset1:76
	v_cvt_f16_f32_e32 v36, v97
	v_cvt_f16_f32_e32 v97, v77
	v_mfma_f32_16x16x16_f16 v[84:87], v[84:85], v[0:1], v[88:91]
	v_cvt_f16_f32_e32 v0, v94
	v_cvt_f16_f32_e32 v1, v95
	v_cvt_f16_f32_e32 v2, v96
	v_cndmask_b32_e64 v96, v76, 0, s[12:13]
	v_cndmask_b32_e64 v0, 0, v0, s[10:11]
	v_cndmask_b32_e64 v37, 0, v1, s[14:15]
	v_cndmask_b32_e64 v1, 0, v2, s[16:17]
	v_cndmask_b32_e64 v2, 0, v36, s[20:21]
	v_pack_b32_f16 v1, v1, v2
	v_pack_b32_f16 v0, v0, v37
	s_nop 0
	s_nop 0
	s_nop 0
	s_nop 0
	s_nop 0
	v_mov_b32_e32 v94, v3
	v_mov_b32_e32 v95, v3
	v_mfma_f32_16x16x16_f16 v[88:91], v[0:1], v[38:39], v[98:101]
	v_cvt_pk_f16_f32 v1, v86, v87
	v_cvt_pk_f16_f32 v0, v84, v85
	v_cvt_f16_f32_e32 v56, v56
	v_cvt_f16_f32_e32 v98, v78
	v_cvt_f16_f32_e32 v99, v79
	s_nop 2
	v_cvt_pk_f16_f32 v91, v90, v91
	v_cvt_pk_f16_f32 v90, v88, v89
	v_cndmask_b32_e64 v97, 0, v97, s[10:11]
	v_cndmask_b32_e64 v98, v98, 0, s[18:19]
	v_mfma_f32_16x16x16_f16 v[84:87], v[0:1], v[90:91], 0
	v_add_u32_e32 v2, 0x800, v231
	v_mov_b32_e32 v90, v3
	v_mov_b32_e32 v91, v3
	v_cndmask_b32_e64 v99, v99, 0, s[22:23]
	s_nop 3
	v_cvt_pk_f16_f32 v1, v86, v87
	v_cvt_pk_f16_f32 v0, v84, v85
	ds_read2_b64 v[84:87], v2 offset0:64 offset1:144
	ds_read_b128 v[76:79], v176 offset:256
	ds_read_b64 v[88:89], v223 offset:5120
	s_nop 0
	s_waitcnt lgkmcnt(2)
	v_mov_b32_e32 v92, v84
	v_mov_b32_e32 v93, v85
	s_waitcnt lgkmcnt(1)
	v_pk_mul_f32 v[42:43], v[42:43], v[78:79]
	v_pk_mul_f32 v[40:41], v[40:41], v[76:77]
	ds_read_b128 v[76:79], v176 offset:320
	ds_read_b64 v[84:85], v224 offset:5120
	v_mfma_f32_16x16x16_f16 v[40:43], v[92:93], v[0:1], v[40:43]
	s_waitcnt lgkmcnt(1)
	v_pk_mul_f32 v[48:49], v[48:49], v[76:77]
	v_add_u32_e32 v76, 0xc00, v231
	v_mfma_f32_16x16x16_f16 v[40:43], v[88:89], v[38:39], v[40:43]
	s_nop 0
	s_nop 0
	v_pk_mul_f32 v[50:51], v[50:51], v[78:79]
	s_nop 0
	s_nop 0
	ds_read2_b64 v[76:79], v76 offset0:96 offset1:176
	v_mfma_f32_16x16x16_f16 v[48:51], v[86:87], v[0:1], v[48:51]
	s_waitcnt lgkmcnt(0)
	v_mov_b32_e32 v92, v76
	v_mfma_f32_16x16x16_f16 v[48:51], v[84:85], v[38:39], v[48:51]
	ds_read_b128 v[84:87], v176 offset:384
	ds_read_b64 v[88:89], v225 offset:5120
	v_mov_b32_e32 v93, v77
	v_pack_b32_f16 v76, v96, v97
	v_cndmask_b32_e64 v96, v56, 0, s[12:13]
	s_waitcnt lgkmcnt(1)
	v_pk_mul_f32 v[46:47], v[46:47], v[86:87]
	v_pk_mul_f32 v[44:45], v[44:45], v[84:85]
	v_cvt_f16_f32_e32 v56, v57
	v_cvt_f16_f32_e32 v57, v58
	v_mfma_f32_16x16x16_f16 v[44:47], v[92:93], v[0:1], v[44:47]
	v_cvt_f16_f32_e32 v58, v59
	v_mov_b32_e32 v92, v78
	v_mov_b32_e32 v93, v79
	s_waitcnt lgkmcnt(0)
	v_mfma_f32_16x16x16_f16 v[44:47], v[88:89], v[38:39], v[44:47]
	ds_read_b128 v[84:87], v176 offset:448
	ds_read_b64 v[88:89], v226 offset:5120
	v_cndmask_b32_e64 v78, v57, 0, s[18:19]
	v_cndmask_b32_e64 v79, v58, 0, s[22:23]
	v_pack_b32_f16 v77, v98, v99
	s_waitcnt lgkmcnt(1)
	v_pk_mul_f32 v[52:53], v[52:53], v[84:85]
	v_cndmask_b32_e64 v84, 0, v56, s[10:11]
	v_mfma_f32_16x16x32_f16 v[56:59], v[72:75], v[60:63], 0
	v_pack_b32_f16 v61, v78, v79
	v_mov_b32_e32 v78, v3
	v_mov_b32_e32 v79, v3
	v_mfma_f32_16x16x32_f16 v[56:59], v[68:71], v[64:67], v[56:59]
	v_mul_f32_e64 v54, v54, v86
	v_mul_f32_e64 v55, v55, v87
	v_pack_b32_f16 v60, v96, v84
	s_nop 0
	s_nop 0
	v_mfma_f32_16x16x16_f16 v[52:55], v[92:93], v[0:1], v[52:55]
	v_mfma_f32_16x16x16_f16 v[56:59], v[76:77], v[0:1], v[56:59]
	s_mul_i32 s52, s31, 3
	s_mul_hi_i32 s53, s31, 3
	v_lshl_add_u64 v[0:1], v[248:249], 0, s[52:53]
	global_store_short v[0:1], v82, off
	s_waitcnt lgkmcnt(0)
	v_mfma_f32_16x16x16_f16 v[52:55], v[88:89], v[38:39], v[52:55]
	s_nop 0
	s_nop 0
	s_nop 0
	v_mfma_f32_16x16x16_f16 v[36:39], v[60:61], v[38:39], v[56:59]
	s_nop 0
	s_mul_i32 s52, s31, 16
	s_mul_hi_i32 s53, s31, 16
	v_lshl_add_u64 v[0:1], v[248:249], 0, s[52:53]
	s_nop 5
	v_cvt_f16_f32_e32 v2, v36
	global_store_short v[0:1], v2, off
	s_nop 0
	s_nop 0
	v_cvt_f16_f32_e32 v2, v37
	s_nop 0
	s_nop 0
	s_mul_i32 s52, s31, 17
	s_mul_hi_i32 s53, s31, 17
	v_lshl_add_u64 v[0:1], v[248:249], 0, s[52:53]
	global_store_short v[0:1], v2, off
	s_nop 0
	s_nop 0
	v_cvt_f16_f32_e32 v2, v38
	s_nop 0
	s_nop 0
	s_mul_i32 s52, s31, 18
	s_mul_hi_i32 s53, s31, 18
	v_lshl_add_u64 v[0:1], v[248:249], 0, s[52:53]
	global_store_short v[0:1], v2, off
	s_nop 0
	s_nop 0
	s_nop 0
	v_cvt_f16_f32_e32 v2, v39
	s_nop 0
	s_mul_i32 s52, s31, 19
	s_mul_hi_i32 s53, s31, 19
	v_lshl_add_u64 v[0:1], v[248:249], 0, s[52:53]
	s_mov_b64 s[26:27], 0
	global_store_short v[0:1], v2, off

.LBB0_935:
	s_or_b64 exec, exec, s[28:29]
	s_waitcnt lgkmcnt(0)
	s_barrier
	ds_read_b128 v[36:39], v216 offset:18432
	ds_read_b128 v[40:43], v216 offset:9216
	ds_read_b128 v[48:51], v216 offset:18496
	s_waitcnt lgkmcnt(1)
	v_mfma_f32_16x16x32_f16 v[52:55], v[40:43], v[36:39], 0
	ds_read_b128 v[56:59], v216 offset:9280
	ds_read_b128 v[60:63], v216 offset:23040
	ds_read_b128 v[64:67], v216 offset:13824
	ds_read_b128 v[68:71], v216 offset:13888
	ds_read_b128 v[72:75], v216 offset:23104
	v_add_u32_e32 v80, 0x1000, v222
	s_waitcnt lgkmcnt(4)
	v_mfma_f32_16x16x32_f16 v[52:55], v[56:59], v[48:51], v[52:55]
	s_nop 0
	s_nop 0
	s_nop 0
	v_mfma_f32_16x16x32_f16 v[44:47], v[36:39], v[40:43], 0
	s_nop 3
	v_cvt_f16_f32_e32 v0, v52
	v_cvt_f16_f32_e32 v1, v54
	v_cvt_f16_f32_e32 v2, v55
	v_mfma_f32_16x16x32_f16 v[44:47], v[48:51], v[56:59], v[44:47]
	v_cndmask_b32_e64 v79, 0, v0, s[12:13]
	v_cvt_f16_f32_e32 v0, v53
	v_cndmask_b32_e64 v54, 0, v1, s[18:19]
	s_waitcnt lgkmcnt(3)
	v_mfma_f32_16x16x32_f16 v[40:43], v[60:63], v[40:43], 0
	v_cndmask_b32_e64 v55, 0, v2, s[22:23]
	s_nop 1
	v_cndmask_b32_e64 v76, 0, v44, s[10:11]
	v_cndmask_b32_e64 v77, 0, v45, s[14:15]
	s_waitcnt lgkmcnt(2)
	v_mfma_f32_16x16x32_f16 v[36:39], v[36:39], v[64:67], 0
	v_cndmask_b32_e64 v52, 0, v46, s[16:17]
	v_cndmask_b32_e64 v78, 0, v47, s[20:21]
	v_cndmask_b32_e64 v53, v0, 0, s[10:11]
	v_mfma_f32_16x16x32_f16 v[44:47], v[60:63], v[64:67], 0
	v_cvt_pk_f16_f32 v1, v52, v78
	v_cvt_pk_f16_f32 v0, v76, v77
	s_nop 0
	s_waitcnt lgkmcnt(0)
	v_mfma_f32_16x16x32_f16 v[60:63], v[72:75], v[56:59], v[40:43]
	v_add_f32_e32 v56, v217, v76
	v_add_f32_e32 v57, v219, v77
	v_add_f32_e32 v58, v220, v52
	v_mfma_f32_16x16x32_f16 v[40:43], v[48:51], v[68:71], v[36:39]
	v_add_f32_e32 v59, v221, v78
	v_cvt_pk_f16_f32 v67, v26, v27
	v_cvt_pk_f16_f32 v66, v24, v25
	v_pack_b32_f16 v37, v54, v55
	v_pack_b32_f16 v36, v79, v53
	s_nop 0
	s_nop 0
	v_mfma_f32_16x16x32_f16 v[52:55], v[72:75], v[68:71], v[44:47]
	ds_read2_b64 v[68:71], v222 offset0:8 offset1:12
	v_cvt_pk_f16_f32 v65, v30, v31
	v_cvt_pk_f16_f32 v64, v28, v29
	v_mfma_f32_16x16x16_f16 v[48:51], v[0:1], v[36:37], 0
	v_cvt_pk_f16_f32 v45, v58, v59
	v_cvt_pk_f16_f32 v44, v56, v57
	s_nop 0
	v_mfma_f32_16x16x16_f16 v[36:39], v[36:37], v[0:1], 0
	s_nop 0
	s_nop 2
	v_cvt_pk_f16_f32 v1, v50, v51
	v_cvt_pk_f16_f32 v0, v48, v49
	s_nop 0
	s_nop 0
	v_cvt_pk_f16_f32 v49, v38, v39
	v_cvt_pk_f16_f32 v48, v36, v37
	v_mfma_f32_16x16x16_f16 v[44:47], v[0:1], v[44:45], v[56:59]
	s_nop 0
	s_nop 0
	s_nop 0
	v_mfma_f32_16x16x16_f16 v[36:39], v[48:49], v[0:1], 0
	v_cvt_pk_f16_f32 v59, v34, v35
	v_cvt_pk_f16_f32 v58, v32, v33
	v_cvt_pk_f16_f32 v57, v22, v23
	v_mfma_f32_16x16x16_f16 v[48:51], v[0:1], v[48:49], 0
	v_cvt_pk_f16_f32 v56, v20, v21
	s_nop 2
	v_cvt_pk_f16_f32 v1, v38, v39
	v_cvt_pk_f16_f32 v0, v36, v37
	v_cvt_pk_f16_f32 v37, v46, v47
	v_cvt_pk_f16_f32 v36, v44, v45
	s_nop 0
	s_nop 0
	v_cvt_f16_f32_e32 v52, v52
	s_add_i32 s27, s26, 1
	v_mfma_f32_16x16x16_f16 v[44:47], v[0:1], v[36:37], v[44:47]
	v_cvt_pk_f16_f32 v37, v50, v51
	v_cvt_pk_f16_f32 v36, v48, v49
	s_nop 0
	s_nop 0
	v_mfma_f32_16x16x16_f16 v[36:39], v[36:37], v[0:1], 0
	s_nop 2
	v_cvt_pk_f16_f32 v1, v46, v47
	v_cvt_pk_f16_f32 v0, v44, v45
	s_nop 2
	v_cvt_pk_f16_f32 v49, v38, v39
	v_cvt_pk_f16_f32 v48, v36, v37
	ds_read2_b64 v[36:39], v222 offset1:4
	s_waitcnt lgkmcnt(0)
	v_mfma_f32_16x16x32_f16 v[36:39], v[36:39], v[56:59], 0
	v_mfma_f32_16x16x16_f16 v[44:47], v[48:49], v[0:1], v[44:47]
	v_cvt_f16_f32_e32 v0, v60
	v_cvt_f16_f32_e32 v1, v61
	v_cvt_f16_f32_e32 v2, v62
	v_cvt_f16_f32_e32 v48, v63
	v_mfma_f32_16x16x32_f16 v[76:79], v[68:71], v[64:67], v[36:39]
	ds_read2_b64 v[72:75], v80 offset0:64 offset1:68
	ds_read2_b64 v[68:71], v80 offset0:72 offset1:76
	s_nop 0
	ds_read2st64_b64 v[36:39], v223 offset0:20 offset1:25
	v_cndmask_b32_e64 v0, 0, v0, s[10:11]
	v_cndmask_b32_e64 v49, 0, v1, s[14:15]
	v_cndmask_b32_e64 v1, 0, v2, s[16:17]
	v_cndmask_b32_e64 v2, 0, v48, s[20:21]
	v_pack_b32_f16 v1, v1, v2
	v_pack_b32_f16 v0, v0, v49
	s_nop 0
	s_waitcnt lgkmcnt(0)
	v_mov_b32_e32 v60, v36
	v_mov_b32_e32 v61, v37
	s_nop 0
	s_nop 0
	v_cvt_f16_f32_e32 v36, v40
	v_cvt_f16_f32_e32 v40, v42
	v_mfma_f32_16x16x16_f16 v[48:51], v[0:1], v[60:61], v[76:79]
	v_cvt_pk_f16_f32 v1, v46, v47
	v_cvt_pk_f16_f32 v0, v44, v45
	v_cvt_f16_f32_e32 v37, v41
	s_nop 0
	s_nop 0
	s_nop 2
	v_cvt_pk_f16_f32 v77, v50, v51
	v_cvt_pk_f16_f32 v76, v48, v49
	v_cndmask_b32_e64 v88, v40, 0, s[18:19]
	v_mfma_f32_16x16x32_f16 v[56:59], v[72:75], v[56:59], 0
	v_cndmask_b32_e64 v36, v36, 0, s[12:13]
	v_cndmask_b32_e64 v37, 0, v37, s[10:11]
	s_nop 0
	v_mfma_f32_16x16x16_f16 v[44:47], v[0:1], v[76:77], 0
	s_nop 0
	v_mfma_f32_16x16x32_f16 v[56:59], v[68:71], v[64:67], v[56:59]
	s_nop 5
	v_cvt_pk_f16_f32 v1, v46, v47
	v_cvt_pk_f16_f32 v0, v44, v45
	ds_read2_b64 v[44:47], v240 offset1:80
	ds_read_b128 v[48:51], v182
	ds_read_b64 v[76:77], v224 offset:5120
	s_waitcnt lgkmcnt(2)
	s_nop 0
	s_nop 0
	s_waitcnt lgkmcnt(1)
	v_pk_mul_f32 v[50:51], v[22:23], v[50:51]
	v_pk_mul_f32 v[48:49], v[20:21], v[48:49]
	s_nop 1
	v_mfma_f32_16x16x16_f16 v[48:51], v[44:45], v[0:1], v[48:51]
	v_cvt_f16_f32_e32 v80, v43
	v_cndmask_b32_e64 v89, v80, 0, s[22:23]
	s_waitcnt lgkmcnt(0)
	v_mfma_f32_16x16x16_f16 v[40:43], v[76:77], v[60:61], v[48:51]
	s_nop 3
	ds_read_b128 v[48:51], v182 offset:64
	ds_read_b64 v[44:45], v225 offset:5120
	s_nop 0
	s_nop 0
	s_nop 0
	s_waitcnt lgkmcnt(1)
	v_pk_mul_f32 v[50:51], v[34:35], v[50:51]
	v_pk_mul_f32 v[48:49], v[32:33], v[48:49]
	s_nop 0
	s_nop 0
	v_mfma_f32_16x16x16_f16 v[48:51], v[46:47], v[0:1], v[48:51]
	ds_read2_b64 v[76:79], v240 offset0:160 offset1:240
	s_waitcnt lgkmcnt(0)
	v_mov_b32_e32 v84, v76
	v_mfma_f32_16x16x16_f16 v[48:51], v[44:45], v[60:61], v[48:51]
	ds_read_b128 v[44:47], v182 offset:128
	ds_read_b64 v[80:81], v226 offset:5120
	v_mov_b32_e32 v85, v77
	v_pack_b32_f16 v77, v88, v89
	s_nop 0
	s_waitcnt lgkmcnt(1)
	v_pk_mul_f32 v[46:47], v[30:31], v[46:47]
	v_pk_mul_f32 v[44:45], v[28:29], v[44:45]
	s_nop 0
	v_pack_b32_f16 v76, v36, v37
	v_mfma_f32_16x16x16_f16 v[44:47], v[84:85], v[0:1], v[44:47]
	v_cndmask_b32_e64 v36, v52, 0, s[12:13]
	v_cvt_f16_f32_e32 v37, v53
	v_cndmask_b32_e64 v37, 0, v37, s[10:11]
	s_waitcnt lgkmcnt(0)
	v_mfma_f32_16x16x16_f16 v[44:47], v[80:81], v[60:61], v[44:47]
	ds_read_b128 v[80:83], v182 offset:192
	ds_read_b64 v[84:85], v227 offset:5120
	v_pack_b32_f16 v72, v36, v37
	ds_read_b128 v[68:71], v228 offset:9216
	ds_read_b128 v[94:97], v228 offset:9280
	s_waitcnt lgkmcnt(3)
	v_pk_mul_f32 v[82:83], v[26:27], v[82:83]
	v_pk_mul_f32 v[80:81], v[24:25], v[80:81]
	ds_read_b128 v[64:67], v228 offset:18432
	ds_read_b128 v[98:101], v228 offset:23104
	v_mfma_f32_16x16x16_f16 v[78:81], v[78:79], v[0:1], v[80:83]
	ds_read_b128 v[90:93], v228 offset:18496
	s_nop 1
	v_cvt_f16_f32_e32 v82, v54
	v_cvt_f16_f32_e32 v83, v55
	s_waitcnt lgkmcnt(5)
	v_mfma_f32_16x16x16_f16 v[52:55], v[84:85], v[60:61], v[78:81]
	ds_read_b128 v[86:89], v228 offset:13824
	s_nop 1
	v_cndmask_b32_e64 v78, v82, 0, s[18:19]
	v_cndmask_b32_e64 v79, v83, 0, s[22:23]
	v_pack_b32_f16 v73, v78, v79
	s_nop 0
	s_nop 0
	v_add_u32_e32 v80, s77, v122
	v_add_u32_e32 v81, s76, v237
	v_mfma_f32_16x16x16_f16 v[56:59], v[76:77], v[0:1], v[56:59]
	ds_read_b128 v[76:79], v228 offset:23040
	v_subrev_u32_e32 v102, 64, v80
	v_add_u32_e32 v0, 0xff, v81
	v_mfma_f32_16x16x16_f16 v[58:61], v[72:73], v[60:61], v[56:59]
	v_cndmask_b32_e64 v0, v0, v102, s[2:3]
	v_add_u32_e32 v0, v0, v175
	s_not_b32 s30, s2
	s_xor_b32 s31, s88, s30
	s_sub_u32 s31, s31, s30
	v_mad_i64_i32 v[0:1], s[28:29], v0, s88, v[126:127]
	v_mov_b64_e32 v[248:249], v[0:1]
	s_waitcnt lgkmcnt(4)
	v_mfma_f32_16x16x32_f16 v[82:85], v[68:71], v[64:67], 0
	s_nop 2
	v_cvt_f16_f32_e32 v2, v58
	v_cvt_f16_f32_e32 v60, v60
	global_store_short v[0:1], v2, off
	s_nop 0
	s_nop 0
	v_cvt_f16_f32_e32 v2, v59
	ds_read_b128 v[56:59], v228 offset:13888
	v_mfma_f32_16x16x32_f16 v[72:75], v[64:67], v[68:71], 0
	s_nop 0
	s_nop 0
	s_mul_i32 s52, s31, 1
	s_mul_hi_i32 s53, s31, 1
	v_lshl_add_u64 v[0:1], v[248:249], 0, s[52:53]
	s_waitcnt lgkmcnt(2)
	v_mfma_f32_16x16x32_f16 v[62:65], v[64:67], v[86:89], 0
	global_store_short v[0:1], v2, off
	s_nop 0
	s_nop 0
	v_mfma_f32_16x16x32_f16 v[82:85], v[94:97], v[90:93], v[82:85]
	s_nop 0
	s_nop 0
	s_waitcnt lgkmcnt(1)
	v_mfma_f32_16x16x32_f16 v[68:71], v[76:79], v[68:71], 0
	v_mfma_f32_16x16x32_f16 v[86:89], v[76:79], v[86:89], 0
	s_nop 2
	v_cvt_f16_f32_e32 v1, v82
	v_cvt_f16_f32_e32 v2, v83
	v_cvt_f16_f32_e32 v66, v85
	v_mfma_f32_16x16x32_f16 v[72:75], v[90:93], v[94:97], v[72:75]
	s_nop 0
	v_cndmask_b32_e64 v66, 0, v66, s[22:23]
	s_waitcnt lgkmcnt(0)
	v_mfma_f32_16x16x32_f16 v[76:79], v[90:93], v[56:59], v[62:65]
	s_nop 0
	s_nop 2
	v_cndmask_b32_e64 v0, 0, v72, s[10:11]
	v_cndmask_b32_e64 v37, 0, v73, s[14:15]
	v_cvt_f16_f32_e32 v63, v84
	v_mfma_f32_16x16x32_f16 v[94:97], v[98:101], v[94:97], v[68:71]
	v_cndmask_b32_e64 v64, 0, v74, s[16:17]
	v_cndmask_b32_e64 v65, 0, v75, s[20:21]
	v_cndmask_b32_e64 v63, 0, v63, s[18:19]
	v_cndmask_b32_e64 v68, 0, v1, s[12:13]
	v_cndmask_b32_e64 v69, v2, 0, s[10:11]
	v_add_f32_e32 v62, v217, v0
	v_cvt_pk_f16_f32 v1, v64, v65
	v_cvt_pk_f16_f32 v0, v0, v37
	s_nop 0
	v_pack_b32_f16 v67, v63, v66
	v_pack_b32_f16 v66, v68, v69
	s_nop 0
	s_nop 0
	v_add_f32_e32 v63, v219, v37
	v_add_f32_e32 v64, v220, v64
	v_mfma_f32_16x16x16_f16 v[70:73], v[0:1], v[66:67], 0
	v_add_f32_e32 v65, v221, v65
	v_cvt_pk_f16_f32 v83, v64, v65
	v_cvt_pk_f16_f32 v82, v62, v63
	v_mfma_f32_16x16x16_f16 v[66:69], v[66:67], v[0:1], 0
	s_nop 0
	s_nop 2
	v_cvt_pk_f16_f32 v0, v70, v71
	s_nop 0
	s_nop 0
	v_cvt_pk_f16_f32 v1, v72, v73
	v_cvt_pk_f16_f32 v69, v68, v69
	v_cvt_pk_f16_f32 v68, v66, v67
	v_mfma_f32_16x16x16_f16 v[62:65], v[0:1], v[82:83], v[62:65]
	s_mul_i32 s52, s31, 2
	s_mul_hi_i32 s53, s31, 2
	v_lshl_add_u64 v[36:37], v[248:249], 0, s[52:53]
	global_store_short v[36:37], v60, off
	v_mfma_f32_16x16x16_f16 v[72:75], v[68:69], v[0:1], 0
	v_cvt_f16_f32_e32 v82, v61
	v_subrev_u32_e32 v36, 61, v80
	v_xad_u32 v37, v102, -4, v168
	v_mfma_f32_16x16x16_f16 v[66:69], v[0:1], v[68:69], 0
	s_nop 0
	v_cvt_pk_f16_f32 v71, v64, v65
	s_nop 1
	v_cvt_pk_f16_f32 v1, v74, v75
	v_cvt_pk_f16_f32 v0, v72, v73
	v_mfma_f32_16x16x32_f16 v[56:59], v[98:101], v[56:59], v[86:89]
	v_cvt_pk_f16_f32 v70, v62, v63
	s_nop 0
	s_nop 0
	v_cvt_pk_f16_f32 v85, v68, v69
	v_cvt_pk_f16_f32 v84, v66, v67
	s_nop 0
	s_nop 0
	v_mfma_f32_16x16x16_f16 v[88:91], v[0:1], v[70:71], v[62:65]
	ds_read2_b64 v[68:71], v229 offset1:4
	ds_read2_b64 v[72:75], v229 offset0:8 offset1:12
	v_cndmask_b32_e64 v36, v37, v36, s[2:3]
	v_mfma_f32_16x16x16_f16 v[60:63], v[84:85], v[0:1], 0
	v_add_u32_e32 v83, v36, v175
	s_nop 2
	v_cvt_pk_f16_f32 v1, v90, v91
	v_cvt_pk_f16_f32 v0, v88, v89
	v_cvt_pk_f16_f32 v67, v54, v55
	v_cvt_pk_f16_f32 v66, v52, v53
	v_cvt_pk_f16_f32 v85, v62, v63
	v_cvt_pk_f16_f32 v84, v60, v61
	v_cvt_pk_f16_f32 v63, v50, v51
	v_cvt_pk_f16_f32 v62, v48, v49
	v_cvt_pk_f16_f32 v61, v42, v43
	v_cvt_pk_f16_f32 v60, v40, v41
	v_cvt_pk_f16_f32 v65, v46, v47
	v_cvt_pk_f16_f32 v64, v44, v45
	s_waitcnt lgkmcnt(1)
	v_mfma_f32_16x16x32_f16 v[68:71], v[68:71], v[60:63], 0
	v_add_u32_e32 v36, 0x1000, v229
	s_nop 0
	v_cvt_f16_f32_e32 v76, v76
	s_waitcnt lgkmcnt(0)
	v_mfma_f32_16x16x32_f16 v[98:101], v[72:75], v[64:67], v[68:71]
	ds_read2_b64 v[72:75], v36 offset0:64 offset1:68
	s_nop 1
	ds_read2_b64 v[68:71], v36 offset0:72 offset1:76
	v_cvt_f16_f32_e32 v36, v97
	v_cvt_f16_f32_e32 v97, v77
	v_mfma_f32_16x16x16_f16 v[84:87], v[84:85], v[0:1], v[88:91]
	v_cvt_f16_f32_e32 v0, v94
	v_cvt_f16_f32_e32 v1, v95
	v_cvt_f16_f32_e32 v2, v96
	v_cndmask_b32_e64 v96, v76, 0, s[12:13]
	v_cndmask_b32_e64 v0, 0, v0, s[10:11]
	v_cndmask_b32_e64 v37, 0, v1, s[14:15]
	v_cndmask_b32_e64 v1, 0, v2, s[16:17]
	v_cndmask_b32_e64 v2, 0, v36, s[20:21]
	v_pack_b32_f16 v1, v1, v2
	v_pack_b32_f16 v0, v0, v37
	s_nop 0
	s_nop 0
	s_nop 0
	s_nop 0
	s_nop 0
	s_nop 0
	s_nop 0
	v_mfma_f32_16x16x16_f16 v[88:91], v[0:1], v[38:39], v[98:101]
	v_cvt_pk_f16_f32 v1, v86, v87
	v_cvt_pk_f16_f32 v0, v84, v85
	v_cvt_f16_f32_e32 v56, v56
	v_cvt_f16_f32_e32 v98, v78
	v_cvt_f16_f32_e32 v99, v79
	s_nop 2
	v_cvt_pk_f16_f32 v91, v90, v91
	v_cvt_pk_f16_f32 v90, v88, v89
	v_cndmask_b32_e64 v97, 0, v97, s[10:11]
	v_cndmask_b32_e64 v98, v98, 0, s[18:19]
	v_mfma_f32_16x16x16_f16 v[84:87], v[0:1], v[90:91], 0
	v_add_u32_e32 v2, 0x800, v240
	s_nop 0
	s_nop 0
	v_cndmask_b32_e64 v99, v99, 0, s[22:23]
	s_nop 3
	v_cvt_pk_f16_f32 v1, v86, v87
	v_cvt_pk_f16_f32 v0, v84, v85
	ds_read2_b64 v[84:87], v2 offset0:64 offset1:144
	ds_read_b128 v[76:79], v182 offset:256
	ds_read_b64 v[88:89], v230 offset:5120
	s_nop 0
	s_waitcnt lgkmcnt(2)
	v_mov_b32_e32 v92, v84
	v_mov_b32_e32 v93, v85
	s_waitcnt lgkmcnt(1)
	v_pk_mul_f32 v[42:43], v[42:43], v[78:79]
	v_pk_mul_f32 v[40:41], v[40:41], v[76:77]
	ds_read_b128 v[76:79], v182 offset:320
	ds_read_b64 v[84:85], v231 offset:5120
	v_mfma_f32_16x16x16_f16 v[40:43], v[92:93], v[0:1], v[40:43]
	s_waitcnt lgkmcnt(1)
	v_pk_mul_f32 v[48:49], v[48:49], v[76:77]
	v_add_u32_e32 v76, 0xc00, v240
	v_mfma_f32_16x16x16_f16 v[40:43], v[88:89], v[38:39], v[40:43]
	s_nop 0
	s_nop 0
	v_pk_mul_f32 v[50:51], v[50:51], v[78:79]
	s_nop 0
	s_nop 0
	ds_read2_b64 v[76:79], v76 offset0:96 offset1:176
	v_mfma_f32_16x16x16_f16 v[48:51], v[86:87], v[0:1], v[48:51]
	s_waitcnt lgkmcnt(0)
	v_mov_b32_e32 v92, v76
	v_mfma_f32_16x16x16_f16 v[48:51], v[84:85], v[38:39], v[48:51]
	ds_read_b128 v[84:87], v182 offset:384
	ds_read_b64 v[88:89], v232 offset:5120
	v_mov_b32_e32 v93, v77
	v_pack_b32_f16 v76, v96, v97
	v_cndmask_b32_e64 v96, v56, 0, s[12:13]
	s_waitcnt lgkmcnt(1)
	v_pk_mul_f32 v[46:47], v[46:47], v[86:87]
	v_pk_mul_f32 v[44:45], v[44:45], v[84:85]
	v_cvt_f16_f32_e32 v56, v57
	v_cvt_f16_f32_e32 v57, v58
	v_mfma_f32_16x16x16_f16 v[44:47], v[92:93], v[0:1], v[44:47]
	v_cvt_f16_f32_e32 v58, v59
	v_mov_b32_e32 v92, v78
	v_mov_b32_e32 v93, v79
	s_waitcnt lgkmcnt(0)
	v_mfma_f32_16x16x16_f16 v[44:47], v[88:89], v[38:39], v[44:47]
	ds_read_b128 v[84:87], v182 offset:448
	ds_read_b64 v[88:89], v233 offset:5120
	v_cndmask_b32_e64 v78, v57, 0, s[18:19]
	v_cndmask_b32_e64 v79, v58, 0, s[22:23]
	v_pack_b32_f16 v77, v98, v99
	s_waitcnt lgkmcnt(1)
	v_pk_mul_f32 v[52:53], v[52:53], v[84:85]
	v_cndmask_b32_e64 v84, 0, v56, s[10:11]
	v_mfma_f32_16x16x32_f16 v[56:59], v[72:75], v[60:63], 0
	v_pack_b32_f16 v61, v78, v79
	v_mov_b32_e32 v78, v3
	v_mov_b32_e32 v79, v3
	v_mfma_f32_16x16x32_f16 v[56:59], v[68:71], v[64:67], v[56:59]
	v_mul_f32_e64 v54, v54, v86
	v_mul_f32_e64 v55, v55, v87
	v_pack_b32_f16 v60, v96, v84
	s_nop 0
	s_nop 0
	v_mfma_f32_16x16x16_f16 v[52:55], v[92:93], v[0:1], v[52:55]
	v_mfma_f32_16x16x16_f16 v[56:59], v[76:77], v[0:1], v[56:59]
	s_mul_i32 s52, s31, 3
	s_mul_hi_i32 s53, s31, 3
	v_lshl_add_u64 v[0:1], v[248:249], 0, s[52:53]
	global_store_short v[0:1], v82, off
	s_waitcnt lgkmcnt(0)
	v_mfma_f32_16x16x16_f16 v[52:55], v[88:89], v[38:39], v[52:55]
	s_nop 0
	s_nop 0
	s_nop 0
	v_mfma_f32_16x16x16_f16 v[36:39], v[60:61], v[38:39], v[56:59]
	s_nop 0
	s_mul_i32 s52, s31, 16
	s_mul_hi_i32 s53, s31, 16
	v_lshl_add_u64 v[0:1], v[248:249], 0, s[52:53]
	s_nop 5
	v_cvt_f16_f32_e32 v2, v36
	global_store_short v[0:1], v2, off
	s_nop 0
	s_nop 0
	v_cvt_f16_f32_e32 v2, v37
	s_nop 0
	s_nop 0
	s_mul_i32 s52, s31, 17
	s_mul_hi_i32 s53, s31, 17
	v_lshl_add_u64 v[0:1], v[248:249], 0, s[52:53]
	global_store_short v[0:1], v2, off
	s_nop 0
	s_nop 0
	v_cvt_f16_f32_e32 v2, v38
	s_nop 0
	s_nop 0
	s_mul_i32 s52, s31, 18
	s_mul_hi_i32 s53, s31, 18
	v_lshl_add_u64 v[0:1], v[248:249], 0, s[52:53]
	global_store_short v[0:1], v2, off
	s_nop 0
	s_nop 0
	s_nop 0
	v_cvt_f16_f32_e32 v2, v39
	s_nop 0
	s_mul_i32 s52, s31, 19
	s_mul_hi_i32 s53, s31, 19
	v_lshl_add_u64 v[0:1], v[248:249], 0, s[52:53]
	s_mov_b64 s[28:29], 0
	global_store_short v[0:1], v2, off

.LBB0_1035:
	s_or_b64 exec, exec, s[26:27]
	s_waitcnt lgkmcnt(0)
	s_barrier
	ds_read_b128 v[36:39], v212 offset:18432
	ds_read_b128 v[40:43], v212 offset:9216
	ds_read_b128 v[48:51], v212 offset:18496
	s_waitcnt lgkmcnt(1)
	v_mfma_f32_16x16x32_f16 v[52:55], v[40:43], v[36:39], 0
	ds_read_b128 v[56:59], v212 offset:9280
	ds_read_b128 v[60:63], v212 offset:23040
	ds_read_b128 v[64:67], v212 offset:13824
	ds_read_b128 v[68:71], v212 offset:13888
	ds_read_b128 v[72:75], v212 offset:23104
	v_add_u32_e32 v80, 0x1000, v217
	s_waitcnt lgkmcnt(4)
	v_mfma_f32_16x16x32_f16 v[52:55], v[56:59], v[48:51], v[52:55]
	s_nop 0
	s_nop 0
	s_nop 0
	v_mfma_f32_16x16x32_f16 v[44:47], v[36:39], v[40:43], 0
	s_nop 3
	v_cvt_f16_f32_e32 v0, v52
	v_cvt_f16_f32_e32 v1, v54
	v_cvt_f16_f32_e32 v2, v55
	v_mfma_f32_16x16x32_f16 v[44:47], v[48:51], v[56:59], v[44:47]
	v_cndmask_b32_e64 v79, 0, v0, s[12:13]
	v_cvt_f16_f32_e32 v0, v53
	v_cndmask_b32_e64 v54, 0, v1, s[18:19]
	s_waitcnt lgkmcnt(3)
	v_mfma_f32_16x16x32_f16 v[40:43], v[60:63], v[40:43], 0
	v_cndmask_b32_e64 v55, 0, v2, s[22:23]
	s_nop 1
	v_cndmask_b32_e64 v76, 0, v44, s[10:11]
	v_cndmask_b32_e64 v77, 0, v45, s[14:15]
	s_waitcnt lgkmcnt(2)
	v_mfma_f32_16x16x32_f16 v[36:39], v[36:39], v[64:67], 0
	v_cndmask_b32_e64 v52, 0, v46, s[16:17]
	v_cndmask_b32_e64 v78, 0, v47, s[20:21]
	v_cndmask_b32_e64 v53, v0, 0, s[10:11]
	v_mfma_f32_16x16x32_f16 v[44:47], v[60:63], v[64:67], 0
	v_cvt_pk_f16_f32 v1, v52, v78
	v_cvt_pk_f16_f32 v0, v76, v77
	s_nop 0
	s_waitcnt lgkmcnt(0)
	v_mfma_f32_16x16x32_f16 v[60:63], v[72:75], v[56:59], v[40:43]
	v_add_f32_e32 v56, v213, v76
	v_add_f32_e32 v57, v214, v77
	v_add_f32_e32 v58, v215, v52
	v_mfma_f32_16x16x32_f16 v[40:43], v[48:51], v[68:71], v[36:39]
	v_add_f32_e32 v59, v216, v78
	v_cvt_pk_f16_f32 v67, v18, v19
	v_cvt_pk_f16_f32 v66, v16, v17
	v_pack_b32_f16 v37, v54, v55
	v_pack_b32_f16 v36, v79, v53
	s_nop 0
	s_nop 0
	v_mfma_f32_16x16x32_f16 v[52:55], v[72:75], v[68:71], v[44:47]
	ds_read2_b64 v[68:71], v217 offset0:8 offset1:12
	v_cvt_pk_f16_f32 v65, v14, v15
	v_cvt_pk_f16_f32 v64, v12, v13
	v_mfma_f32_16x16x16_f16 v[48:51], v[0:1], v[36:37], 0
	v_cvt_pk_f16_f32 v45, v58, v59
	v_cvt_pk_f16_f32 v44, v56, v57
	s_nop 0
	v_mfma_f32_16x16x16_f16 v[36:39], v[36:37], v[0:1], 0
	s_nop 0
	s_nop 2
	v_cvt_pk_f16_f32 v1, v50, v51
	v_cvt_pk_f16_f32 v0, v48, v49
	s_nop 0
	s_nop 0
	v_cvt_pk_f16_f32 v49, v38, v39
	v_cvt_pk_f16_f32 v48, v36, v37
	v_mfma_f32_16x16x16_f16 v[44:47], v[0:1], v[44:45], v[56:59]
	s_nop 0
	s_nop 0
	s_nop 0
	v_mfma_f32_16x16x16_f16 v[36:39], v[48:49], v[0:1], 0
	v_cvt_pk_f16_f32 v59, v10, v11
	v_cvt_pk_f16_f32 v58, v8, v9
	v_cvt_pk_f16_f32 v57, v6, v7
	v_mfma_f32_16x16x16_f16 v[48:51], v[0:1], v[48:49], 0
	v_cvt_pk_f16_f32 v56, v4, v5
	s_nop 2
	v_cvt_pk_f16_f32 v1, v38, v39
	v_cvt_pk_f16_f32 v0, v36, v37
	v_cvt_pk_f16_f32 v37, v46, v47
	v_cvt_pk_f16_f32 v36, v44, v45
	s_nop 0
	s_nop 0
	v_cvt_f16_f32_e32 v52, v52
	s_add_i32 s28, s76, 1
	v_mfma_f32_16x16x16_f16 v[44:47], v[0:1], v[36:37], v[44:47]
	v_cvt_pk_f16_f32 v37, v50, v51
	v_cvt_pk_f16_f32 v36, v48, v49
	s_nop 0
	s_nop 0
	v_mfma_f32_16x16x16_f16 v[36:39], v[36:37], v[0:1], 0
	s_nop 2
	v_cvt_pk_f16_f32 v1, v46, v47
	v_cvt_pk_f16_f32 v0, v44, v45
	s_nop 2
	v_cvt_pk_f16_f32 v49, v38, v39
	v_cvt_pk_f16_f32 v48, v36, v37
	ds_read2_b64 v[36:39], v217 offset1:4
	s_waitcnt lgkmcnt(0)
	v_mfma_f32_16x16x32_f16 v[36:39], v[36:39], v[56:59], 0
	v_mfma_f32_16x16x16_f16 v[44:47], v[48:49], v[0:1], v[44:47]
	v_cvt_f16_f32_e32 v0, v60
	v_cvt_f16_f32_e32 v1, v61
	v_cvt_f16_f32_e32 v2, v62
	v_cvt_f16_f32_e32 v48, v63
	v_mfma_f32_16x16x32_f16 v[76:79], v[68:71], v[64:67], v[36:39]
	ds_read2_b64 v[72:75], v80 offset0:64 offset1:68
	ds_read2_b64 v[68:71], v80 offset0:72 offset1:76
	s_nop 0
	ds_read2st64_b64 v[36:39], v218 offset0:20 offset1:25
	v_cndmask_b32_e64 v0, 0, v0, s[10:11]
	v_cndmask_b32_e64 v49, 0, v1, s[14:15]
	v_cndmask_b32_e64 v1, 0, v2, s[16:17]
	v_cndmask_b32_e64 v2, 0, v48, s[20:21]
	v_pack_b32_f16 v1, v1, v2
	v_pack_b32_f16 v0, v0, v49
	s_nop 0
	s_waitcnt lgkmcnt(0)
	v_mov_b32_e32 v60, v36
	v_mov_b32_e32 v61, v37
	s_nop 0
	s_nop 0
	v_cvt_f16_f32_e32 v36, v40
	v_cvt_f16_f32_e32 v40, v42
	v_mfma_f32_16x16x16_f16 v[48:51], v[0:1], v[60:61], v[76:79]
	v_cvt_pk_f16_f32 v1, v46, v47
	v_cvt_pk_f16_f32 v0, v44, v45
	v_cvt_f16_f32_e32 v37, v41
	s_nop 0
	s_nop 0
	s_nop 2
	v_cvt_pk_f16_f32 v77, v50, v51
	v_cvt_pk_f16_f32 v76, v48, v49
	v_cndmask_b32_e64 v88, v40, 0, s[18:19]
	v_mfma_f32_16x16x32_f16 v[56:59], v[72:75], v[56:59], 0
	v_cndmask_b32_e64 v36, v36, 0, s[12:13]
	v_cndmask_b32_e64 v37, 0, v37, s[10:11]
	s_nop 0
	v_mfma_f32_16x16x16_f16 v[44:47], v[0:1], v[76:77], 0
	s_nop 0
	v_mfma_f32_16x16x32_f16 v[56:59], v[68:71], v[64:67], v[56:59]
	s_nop 5
	v_cvt_pk_f16_f32 v1, v46, v47
	v_cvt_pk_f16_f32 v0, v44, v45
	ds_read2_b64 v[44:47], v233 offset1:80
	ds_read_b128 v[48:51], v178
	ds_read_b64 v[76:77], v219 offset:5120
	s_waitcnt lgkmcnt(2)
	s_nop 0
	s_nop 0
	s_waitcnt lgkmcnt(1)
	v_pk_mul_f32 v[50:51], v[6:7], v[50:51]
	v_pk_mul_f32 v[48:49], v[4:5], v[48:49]
	s_nop 1
	v_mfma_f32_16x16x16_f16 v[48:51], v[44:45], v[0:1], v[48:51]
	v_cvt_f16_f32_e32 v80, v43
	v_cndmask_b32_e64 v89, v80, 0, s[22:23]
	s_waitcnt lgkmcnt(0)
	v_mfma_f32_16x16x16_f16 v[40:43], v[76:77], v[60:61], v[48:51]
	s_nop 3
	ds_read_b128 v[48:51], v178 offset:64
	ds_read_b64 v[44:45], v220 offset:5120
	s_nop 0
	s_nop 0
	s_nop 0
	s_waitcnt lgkmcnt(1)
	v_pk_mul_f32 v[50:51], v[10:11], v[50:51]
	v_pk_mul_f32 v[48:49], v[8:9], v[48:49]
	s_nop 0
	s_nop 0
	v_mfma_f32_16x16x16_f16 v[48:51], v[46:47], v[0:1], v[48:51]
	ds_read2_b64 v[76:79], v233 offset0:160 offset1:240
	s_waitcnt lgkmcnt(0)
	v_mov_b32_e32 v84, v76
	v_mfma_f32_16x16x16_f16 v[48:51], v[44:45], v[60:61], v[48:51]
	ds_read_b128 v[44:47], v178 offset:128
	ds_read_b64 v[80:81], v221 offset:5120
	v_mov_b32_e32 v85, v77
	v_pack_b32_f16 v77, v88, v89
	s_nop 0
	s_waitcnt lgkmcnt(1)
	v_pk_mul_f32 v[46:47], v[14:15], v[46:47]
	v_pk_mul_f32 v[44:45], v[12:13], v[44:45]
	s_nop 0
	v_pack_b32_f16 v76, v36, v37
	v_mfma_f32_16x16x16_f16 v[44:47], v[84:85], v[0:1], v[44:47]
	v_cndmask_b32_e64 v36, v52, 0, s[12:13]
	v_cvt_f16_f32_e32 v37, v53
	v_cndmask_b32_e64 v37, 0, v37, s[10:11]
	s_waitcnt lgkmcnt(0)
	v_mfma_f32_16x16x16_f16 v[44:47], v[80:81], v[60:61], v[44:47]
	ds_read_b128 v[80:83], v178 offset:192
	ds_read_b64 v[84:85], v222 offset:5120
	v_pack_b32_f16 v72, v36, v37
	ds_read_b128 v[68:71], v223 offset:9216
	ds_read_b128 v[94:97], v223 offset:9280
	s_waitcnt lgkmcnt(3)
	v_pk_mul_f32 v[82:83], v[18:19], v[82:83]
	v_pk_mul_f32 v[80:81], v[16:17], v[80:81]
	ds_read_b128 v[64:67], v223 offset:18432
	ds_read_b128 v[98:101], v223 offset:23104
	v_mfma_f32_16x16x16_f16 v[78:81], v[78:79], v[0:1], v[80:83]
	ds_read_b128 v[90:93], v223 offset:18496
	s_nop 1
	v_cvt_f16_f32_e32 v82, v54
	v_cvt_f16_f32_e32 v83, v55
	s_waitcnt lgkmcnt(5)
	v_mfma_f32_16x16x16_f16 v[52:55], v[84:85], v[60:61], v[78:81]
	ds_read_b128 v[86:89], v223 offset:13824
	s_nop 1
	v_cndmask_b32_e64 v78, v82, 0, s[18:19]
	v_cndmask_b32_e64 v79, v83, 0, s[22:23]
	v_pack_b32_f16 v73, v78, v79
	s_nop 0
	s_nop 0
	v_add_u32_e32 v80, s69, v153
	v_add_u32_e32 v81, s68, v232
	v_mfma_f32_16x16x16_f16 v[56:59], v[76:77], v[0:1], v[56:59]
	ds_read_b128 v[76:79], v223 offset:23040
	v_subrev_u32_e32 v102, 64, v80
	v_add_u32_e32 v0, 0x7ff, v81
	v_mfma_f32_16x16x16_f16 v[58:61], v[72:73], v[60:61], v[56:59]
	v_cndmask_b32_e64 v0, v0, v102, s[2:3]
	v_add_u32_e32 v0, v0, v151
	s_not_b32 s30, s2
	s_xor_b32 s31, s88, s30
	s_sub_u32 s31, s31, s30
	v_mad_i64_i32 v[0:1], s[26:27], v0, s88, v[122:123]
	v_mov_b64_e32 v[248:249], v[0:1]
	s_waitcnt lgkmcnt(4)
	v_mfma_f32_16x16x32_f16 v[82:85], v[68:71], v[64:67], 0
	s_nop 2
	v_cvt_f16_f32_e32 v2, v58
	v_cvt_f16_f32_e32 v60, v60
	global_store_short v[0:1], v2, off
	s_nop 0
	s_nop 0
	v_cvt_f16_f32_e32 v2, v59
	ds_read_b128 v[56:59], v223 offset:13888
	v_mfma_f32_16x16x32_f16 v[72:75], v[64:67], v[68:71], 0
	s_nop 0
	s_nop 0
	s_mul_i32 s52, s31, 1
	s_mul_hi_i32 s53, s31, 1
	v_lshl_add_u64 v[0:1], v[248:249], 0, s[52:53]
	s_waitcnt lgkmcnt(2)
	v_mfma_f32_16x16x32_f16 v[62:65], v[64:67], v[86:89], 0
	global_store_short v[0:1], v2, off
	s_nop 0
	s_nop 0
	v_mfma_f32_16x16x32_f16 v[82:85], v[94:97], v[90:93], v[82:85]
	s_nop 0
	s_nop 0
	s_waitcnt lgkmcnt(1)
	v_mfma_f32_16x16x32_f16 v[68:71], v[76:79], v[68:71], 0
	v_mfma_f32_16x16x32_f16 v[86:89], v[76:79], v[86:89], 0
	s_nop 2
	v_cvt_f16_f32_e32 v1, v82
	v_cvt_f16_f32_e32 v2, v83
	v_cvt_f16_f32_e32 v66, v85
	v_mfma_f32_16x16x32_f16 v[72:75], v[90:93], v[94:97], v[72:75]
	s_nop 0
	v_cndmask_b32_e64 v66, 0, v66, s[22:23]
	s_waitcnt lgkmcnt(0)
	v_mfma_f32_16x16x32_f16 v[76:79], v[90:93], v[56:59], v[62:65]
	s_nop 0
	s_nop 2
	v_cndmask_b32_e64 v0, 0, v72, s[10:11]
	v_cndmask_b32_e64 v37, 0, v73, s[14:15]
	v_cvt_f16_f32_e32 v63, v84
	v_mfma_f32_16x16x32_f16 v[94:97], v[98:101], v[94:97], v[68:71]
	v_cndmask_b32_e64 v64, 0, v74, s[16:17]
	v_cndmask_b32_e64 v65, 0, v75, s[20:21]
	v_cndmask_b32_e64 v63, 0, v63, s[18:19]
	v_cndmask_b32_e64 v68, 0, v1, s[12:13]
	v_cndmask_b32_e64 v69, v2, 0, s[10:11]
	v_add_f32_e32 v62, v213, v0
	v_cvt_pk_f16_f32 v1, v64, v65
	v_cvt_pk_f16_f32 v0, v0, v37
	s_nop 0
	v_pack_b32_f16 v67, v63, v66
	v_pack_b32_f16 v66, v68, v69
	s_nop 0
	s_nop 0
	v_add_f32_e32 v63, v214, v37
	v_add_f32_e32 v64, v215, v64
	v_mfma_f32_16x16x16_f16 v[70:73], v[0:1], v[66:67], 0
	v_add_f32_e32 v65, v216, v65
	v_cvt_pk_f16_f32 v83, v64, v65
	v_cvt_pk_f16_f32 v82, v62, v63
	v_mfma_f32_16x16x16_f16 v[66:69], v[66:67], v[0:1], 0
	s_nop 0
	s_nop 2
	v_cvt_pk_f16_f32 v0, v70, v71
	s_nop 0
	s_nop 0
	v_cvt_pk_f16_f32 v1, v72, v73
	v_cvt_pk_f16_f32 v69, v68, v69
	v_cvt_pk_f16_f32 v68, v66, v67
	v_mfma_f32_16x16x16_f16 v[62:65], v[0:1], v[82:83], v[62:65]
	s_mul_i32 s52, s31, 2
	s_mul_hi_i32 s53, s31, 2
	v_lshl_add_u64 v[36:37], v[248:249], 0, s[52:53]
	global_store_short v[36:37], v60, off
	v_mfma_f32_16x16x16_f16 v[72:75], v[68:69], v[0:1], 0
	v_cvt_f16_f32_e32 v82, v61
	v_subrev_u32_e32 v36, 61, v80
	v_xad_u32 v37, v102, -4, v172
	v_mfma_f32_16x16x16_f16 v[66:69], v[0:1], v[68:69], 0
	s_nop 0
	v_cvt_pk_f16_f32 v71, v64, v65
	s_nop 1
	v_cvt_pk_f16_f32 v1, v74, v75
	v_cvt_pk_f16_f32 v0, v72, v73
	v_mfma_f32_16x16x32_f16 v[56:59], v[98:101], v[56:59], v[86:89]
	v_cvt_pk_f16_f32 v70, v62, v63
	s_nop 0
	s_nop 0
	v_cvt_pk_f16_f32 v85, v68, v69
	v_cvt_pk_f16_f32 v84, v66, v67
	s_nop 0
	s_nop 0
	v_mfma_f32_16x16x16_f16 v[88:91], v[0:1], v[70:71], v[62:65]
	ds_read2_b64 v[68:71], v224 offset1:4
	ds_read2_b64 v[72:75], v224 offset0:8 offset1:12
	v_cndmask_b32_e64 v36, v37, v36, s[2:3]
	v_mfma_f32_16x16x16_f16 v[60:63], v[84:85], v[0:1], 0
	v_add_u32_e32 v83, v36, v151
	s_nop 2
	v_cvt_pk_f16_f32 v1, v90, v91
	v_cvt_pk_f16_f32 v0, v88, v89
	v_cvt_pk_f16_f32 v67, v54, v55
	v_cvt_pk_f16_f32 v66, v52, v53
	v_cvt_pk_f16_f32 v85, v62, v63
	v_cvt_pk_f16_f32 v84, v60, v61
	v_cvt_pk_f16_f32 v63, v50, v51
	v_cvt_pk_f16_f32 v62, v48, v49
	v_cvt_pk_f16_f32 v61, v42, v43
	v_cvt_pk_f16_f32 v60, v40, v41
	v_cvt_pk_f16_f32 v65, v46, v47
	v_cvt_pk_f16_f32 v64, v44, v45
	s_waitcnt lgkmcnt(1)
	v_mfma_f32_16x16x32_f16 v[68:71], v[68:71], v[60:63], 0
	v_add_u32_e32 v36, 0x1000, v224
	s_nop 0
	v_cvt_f16_f32_e32 v76, v76
	s_waitcnt lgkmcnt(0)
	v_mfma_f32_16x16x32_f16 v[98:101], v[72:75], v[64:67], v[68:71]
	ds_read2_b64 v[72:75], v36 offset0:64 offset1:68
	s_nop 1
	ds_read2_b64 v[68:71], v36 offset0:72 offset1:76
	v_cvt_f16_f32_e32 v36, v97
	v_cvt_f16_f32_e32 v97, v77
	v_mfma_f32_16x16x16_f16 v[84:87], v[84:85], v[0:1], v[88:91]
	v_cvt_f16_f32_e32 v0, v94
	v_cvt_f16_f32_e32 v1, v95
	v_cvt_f16_f32_e32 v2, v96
	v_cndmask_b32_e64 v96, v76, 0, s[12:13]
	v_cndmask_b32_e64 v0, 0, v0, s[10:11]
	v_cndmask_b32_e64 v37, 0, v1, s[14:15]
	v_cndmask_b32_e64 v1, 0, v2, s[16:17]
	v_cndmask_b32_e64 v2, 0, v36, s[20:21]
	v_pack_b32_f16 v1, v1, v2
	v_pack_b32_f16 v0, v0, v37
	s_nop 0
	s_nop 0
	s_nop 0
	s_nop 0
	s_nop 0
	s_nop 0
	s_nop 0
	v_mfma_f32_16x16x16_f16 v[88:91], v[0:1], v[38:39], v[98:101]
	v_cvt_pk_f16_f32 v1, v86, v87
	v_cvt_pk_f16_f32 v0, v84, v85
	v_cvt_f16_f32_e32 v56, v56
	v_cvt_f16_f32_e32 v98, v78
	v_cvt_f16_f32_e32 v99, v79
	s_nop 2
	v_cvt_pk_f16_f32 v91, v90, v91
	v_cvt_pk_f16_f32 v90, v88, v89
	v_cndmask_b32_e64 v97, 0, v97, s[10:11]
	v_cndmask_b32_e64 v98, v98, 0, s[18:19]
	v_mfma_f32_16x16x16_f16 v[84:87], v[0:1], v[90:91], 0
	v_add_u32_e32 v2, 0x800, v233
	s_nop 0
	s_nop 0
	v_cndmask_b32_e64 v99, v99, 0, s[22:23]
	s_nop 3
	v_cvt_pk_f16_f32 v1, v86, v87
	v_cvt_pk_f16_f32 v0, v84, v85
	ds_read2_b64 v[84:87], v2 offset0:64 offset1:144
	ds_read_b128 v[76:79], v178 offset:256
	ds_read_b64 v[88:89], v225 offset:5120
	s_nop 0
	s_waitcnt lgkmcnt(2)
	v_mov_b32_e32 v92, v84
	v_mov_b32_e32 v93, v85
	s_waitcnt lgkmcnt(1)
	v_pk_mul_f32 v[42:43], v[42:43], v[78:79]
	v_pk_mul_f32 v[40:41], v[40:41], v[76:77]
	ds_read_b128 v[76:79], v178 offset:320
	ds_read_b64 v[84:85], v226 offset:5120
	v_mfma_f32_16x16x16_f16 v[40:43], v[92:93], v[0:1], v[40:43]
	s_waitcnt lgkmcnt(1)
	v_pk_mul_f32 v[48:49], v[48:49], v[76:77]
	v_add_u32_e32 v76, 0xc00, v233
	v_mfma_f32_16x16x16_f16 v[40:43], v[88:89], v[38:39], v[40:43]
	s_nop 0
	s_nop 0
	v_pk_mul_f32 v[50:51], v[50:51], v[78:79]
	s_nop 0
	s_nop 0
	ds_read2_b64 v[76:79], v76 offset0:96 offset1:176
	v_mfma_f32_16x16x16_f16 v[48:51], v[86:87], v[0:1], v[48:51]
	s_waitcnt lgkmcnt(0)
	v_mov_b32_e32 v92, v76
	v_mfma_f32_16x16x16_f16 v[48:51], v[84:85], v[38:39], v[48:51]
	ds_read_b128 v[84:87], v178 offset:384
	ds_read_b64 v[88:89], v227 offset:5120
	v_mov_b32_e32 v93, v77
	v_pack_b32_f16 v76, v96, v97
	v_cndmask_b32_e64 v96, v56, 0, s[12:13]
	s_waitcnt lgkmcnt(1)
	v_pk_mul_f32 v[46:47], v[46:47], v[86:87]
	v_pk_mul_f32 v[44:45], v[44:45], v[84:85]
	v_cvt_f16_f32_e32 v56, v57
	v_cvt_f16_f32_e32 v57, v58
	v_mfma_f32_16x16x16_f16 v[44:47], v[92:93], v[0:1], v[44:47]
	v_cvt_f16_f32_e32 v58, v59
	v_mov_b32_e32 v92, v78
	v_mov_b32_e32 v93, v79
	s_waitcnt lgkmcnt(0)
	v_mfma_f32_16x16x16_f16 v[44:47], v[88:89], v[38:39], v[44:47]
	ds_read_b128 v[84:87], v178 offset:448
	ds_read_b64 v[88:89], v228 offset:5120
	v_cndmask_b32_e64 v78, v57, 0, s[18:19]
	v_cndmask_b32_e64 v79, v58, 0, s[22:23]
	v_pack_b32_f16 v77, v98, v99
	s_waitcnt lgkmcnt(1)
	v_pk_mul_f32 v[52:53], v[52:53], v[84:85]
	v_cndmask_b32_e64 v84, 0, v56, s[10:11]
	v_mfma_f32_16x16x32_f16 v[56:59], v[72:75], v[60:63], 0
	v_pack_b32_f16 v61, v78, v79
	v_mov_b32_e32 v78, v3
	v_mov_b32_e32 v79, v3
	v_mfma_f32_16x16x32_f16 v[56:59], v[68:71], v[64:67], v[56:59]
	v_mul_f32_e64 v54, v54, v86
	v_mul_f32_e64 v55, v55, v87
	v_pack_b32_f16 v60, v96, v84
	s_nop 0
	s_nop 0
	v_mfma_f32_16x16x16_f16 v[52:55], v[92:93], v[0:1], v[52:55]
	v_mfma_f32_16x16x16_f16 v[56:59], v[76:77], v[0:1], v[56:59]
	s_mul_i32 s52, s31, 3
	s_mul_hi_i32 s53, s31, 3
	v_lshl_add_u64 v[0:1], v[248:249], 0, s[52:53]
	global_store_short v[0:1], v82, off
	s_waitcnt lgkmcnt(0)
	v_mfma_f32_16x16x16_f16 v[52:55], v[88:89], v[38:39], v[52:55]
	s_nop 0
	s_nop 0
	s_nop 0
	v_mfma_f32_16x16x16_f16 v[36:39], v[60:61], v[38:39], v[56:59]
	s_nop 0
	s_mul_i32 s52, s31, 16
	s_mul_hi_i32 s53, s31, 16
	v_lshl_add_u64 v[0:1], v[248:249], 0, s[52:53]
	s_nop 5
	v_cvt_f16_f32_e32 v2, v36
	global_store_short v[0:1], v2, off
	s_nop 0
	s_nop 0
	v_cvt_f16_f32_e32 v2, v37
	s_nop 0
	s_nop 0
	s_mul_i32 s52, s31, 17
	s_mul_hi_i32 s53, s31, 17
	v_lshl_add_u64 v[0:1], v[248:249], 0, s[52:53]
	global_store_short v[0:1], v2, off
	s_nop 0
	s_nop 0
	v_cvt_f16_f32_e32 v2, v38
	s_nop 0
	s_nop 0
	s_mul_i32 s52, s31, 18
	s_mul_hi_i32 s53, s31, 18
	v_lshl_add_u64 v[0:1], v[248:249], 0, s[52:53]
	global_store_short v[0:1], v2, off
	s_nop 0
	s_nop 0
	s_nop 0
	v_cvt_f16_f32_e32 v2, v39
	s_nop 0
	s_mul_i32 s52, s31, 19
	s_mul_hi_i32 s53, s31, 19
	v_lshl_add_u64 v[0:1], v[248:249], 0, s[52:53]
	s_mov_b64 s[26:27], 0
	global_store_short v[0:1], v2, off
